# P8: 8 of the next tile's 12 first operand ds_reads issued from the middle of the prompt epilogue (registers dead after the n=0 pass); tile start skips them via a scalar flag
# baseline (speedup 1.0000x reference)
.LBB0_1093:
	s_lshl_b32 s4, s4, 5
	s_and_b32 s10, s4, 0x60
	s_lshl_b32 s6, s55, 13
	s_lshl_b32 s7, s10, 7
	s_add_u32 s22, s18, 0xa5b8000
	s_addc_u32 s23, s19, 0
	s_add_u32 s24, s18, 0x15b38000
	s_addc_u32 s25, s19, 0
	s_add_u32 s26, s18, 0x17138000
	s_addc_u32 s27, s19, 0
	s_add_u32 s28, s18, 0x18738000
	s_addc_u32 s29, s19, 0
	s_ashr_i32 s63, s33, 31
	s_add_u32 s30, s12, 0xb000
	s_addc_u32 s31, s13, 0
	s_add_u32 s34, s12, 0x16000
	s_mov_b64 s[36:37], 0x80
	s_addc_u32 s35, s13, 0
	s_add_i32 m0, s21, 0x18000
	v_lshl_add_u64 v[8:9], v[8:9], 0, s[36:37]
	s_waitcnt vmcnt(4)
	s_barrier
	global_load_lds_dwordx4 v[8:9], off
	v_lshl_add_u64 v[6:7], v[6:7], 0, s[36:37]
	s_add_i32 m0, s21, 0x1a000
	s_add_i32 s64, s21, 0x8000
	s_add_i32 s65, s21, 0xa000
	global_load_lds_dwordx4 v[6:7], off
	v_lshl_add_u64 v[4:5], v[4:5], 0, s[36:37]
	s_mov_b32 m0, s64
	s_add_u32 s4, s50, 0x80080
	global_load_lds_dwordx4 v[4:5], off
	v_lshl_add_u64 v[2:3], v[2:3], 0, s[36:37]
	s_mov_b32 m0, s65
	s_addc_u32 s5, s51, 0
	global_load_lds_dwordx4 v[2:3], off
	s_add_i32 m0, s21, 0x1c000
	v_lshl_add_u64 v[2:3], s[4:5], 0, v[162:163]
	global_load_lds_dwordx4 v[2:3], off
	v_lshl_add_u64 v[2:3], s[4:5], 0, v[164:165]
	s_add_i32 m0, s21, 0x1e000
	v_lshlrev_b32_e32 v4, 6, v10
	global_load_lds_dwordx4 v[2:3], off
	v_bfe_u32 v2, v10, 4, 2
	v_lshlrev_b32_e32 v3, 4, v2
	s_movk_i32 s4, 0x3c0
	v_lshlrev_b32_e32 v5, 2, v10
	v_and_or_b32 v4, v4, s4, v3
	v_and_b32_e32 v5, 32, v5
	v_lshl_or_b32 v239, v2, 2, s10
	v_lshlrev_b32_e32 v2, 9, v10
	v_bitop3_b32 v236, s7, v4, v5 bitop3:0xf6
	v_and_b32_e32 v2, 0x70000, v2
	v_lshlrev_b32_e32 v4, 12, v13
	v_or3_b32 v2, v11, v2, v4
	v_and_b32_e32 v1, 15, v10
	v_add_u32_e32 v166, v2, v12
	v_lshlrev_b32_e32 v2, 5, v14
	v_lshl_or_b32 v3, v1, 6, v3
	s_waitcnt vmcnt(6)
	v_and_b32_e32 v2, 0xf0000, v2
	v_lshl_or_b32 v6, s55, 6, v1
	v_bitop3_b32 v3, v3, s6, v5 bitop3:0xde
	v_or3_b32 v2, v11, v2, v4
	s_add_i32 s68, 0, 0x10000
	s_add_i32 s69, 0, 0x14000
	v_cmp_gt_u32_e64 s[4:5], 2, v1
	v_cmp_lt_u32_e64 s[6:7], 13, v1
	v_add_u32_e32 v237, -14, v1
	v_cmp_lt_u32_e64 s[8:9], 1, v1
	v_add_u32_e32 v238, 0xffffc000, v6
	s_ashr_i32 s66, s3, 31
	v_mov_b32_e32 v167, v163
	v_add_u32_e32 v170, v2, v12
	v_mov_b32_e32 v171, v163
	v_mov_b64_e32 v[172:173], 0xbb0
	v_mov_b64_e32 v[174:175], 0xbaf
	s_movk_i32 s67, 0x16c
	s_mov_b32 s87, 28
	v_and_b32_e32 v245, 31, v0
	v_lshlrev_b32_e32 v245, 4, v245
	v_bfe_u32 v250, v0, 5, 1
	v_mul_u32_u24_e32 v250, 0x5800, v250
	v_add_u32_e32 v245, v245, v250
	v_lshlrev_b32_e32 v250, 2, v239
	s_mov_b32 s86, 0x20000
	s_mov_b32 s32, 0
	v_add_u32_e32 v240, s68, v236
	v_add_u32_e32 v241, 0, v3
	v_add_u32_e32 v242, s69, v236
	s_movk_i32 s70, 0x5000
	s_mov_b32 s71, 0xb000
	s_movk_i32 s72, 0x2c00
	s_barrier
	s_branch .LBB0_1095

.LBB0_1097:
	v_add_u32_e32 v168, 0x18000, v236
	v_add_u32_e32 v169, 0x1c000, v236
	s_cmp_eq_u32 s32, 1
	s_mov_b32 s32, 0
	s_cbranch_scc1 .Lp8_skip_pre
	ds_read_b128 v[130:133], v240
	ds_read_b128 v[134:137], v240 offset:1024
	ds_read_b128 v[138:141], v240 offset:2048
	ds_read_b128 v[142:145], v240 offset:3072
	ds_read_b128 v[146:149], v241
	ds_read_b128 v[150:153], v241 offset:1024
	ds_read_b128 v[154:157], v241 offset:2048
	ds_read_b128 v[158:161], v241 offset:3072
.Lp8_skip_pre:
	ds_read_b128 v[176:179], v241 offset:4096
	ds_read_b128 v[180:183], v241 offset:5120
	ds_read_b128 v[184:187], v241 offset:6144
	ds_read_b128 v[188:191], v241 offset:7168
	s_ashr_i32 s41, s40, 31
	v_cmp_lt_i64_e32 vcc, s[42:43], v[172:173]
	s_lshl_b64 s[42:43], s[40:41], 20
	s_add_u32 s42, s57, s42
	s_addc_u32 s43, s58, s43
	s_add_u32 s42, s42, s89
	s_addc_u32 s43, s43, 0
	s_and_b64 s[44:45], vcc, exec
	s_cselect_b32 s41, s43, s49
	s_cselect_b32 s47, s42, s48
	s_ashr_i32 s39, s38, 31
	s_lshl_b64 s[44:45], s[38:39], 20
	s_add_u32 s44, s18, s44
	s_addc_u32 s45, s19, s45
	s_add_u32 s44, s44, s89
	s_addc_u32 s45, s45, 0
	s_and_b64 s[52:53], vcc, exec
	s_cselect_b32 s39, s45, s51
	s_cselect_b32 s73, s44, s50
	s_add_u32 s48, s48, 0x80080
	s_addc_u32 s49, s49, 0
	s_add_u32 s74, s50, 0x100
	s_addc_u32 s75, s51, 0
	s_mov_b32 s80, -2
	s_cmpk_gt_u32 s56, 0xfff
	s_cbranch_scc1 .Lp8_nostage
	s_lshr_b32 s84, s56, 10
	s_mul_i32 s85, s84, 0xb000
	s_add_u32 s94, s12, s85
	s_addc_u32 s95, s13, 0
	s_cmp_eq_u32 s84, 3
	s_cselect_b32 s94, s14, s94
	s_cselect_b32 s95, s15, s95
	s_lshl_b32 s85, s46, 9
	s_add_u32 s94, s94, s85
	s_addc_u32 s95, s95, 0
	s_add_i32 m0, s86, s56
	s_nop 0
	global_load_lds_dwordx4 v245, s[94:95]

.Lp8_loop_exit:
	v_lshl_or_b32 v176, s46, 7, v239
	s_cmp_gt_i32 s20, 63
	v_ashrrev_i32_e32 v177, 31, v176
	s_mov_b64 s[46:47], -1
	s_cbranch_scc1 .LBB0_1141
	v_add_u32_e32 v251, s86, v250
	ds_read_b128 v[130:133], v251
	ds_read_b128 v[146:149], v251 offset:512
	ds_read_b128 v[134:137], v251 offset:1024
	ds_read_b128 v[150:153], v251 offset:1536
	ds_read_b128 v[138:141], v251 offset:2048
	ds_read_b128 v[154:157], v251 offset:2560
	ds_read_b128 v[142:145], v251 offset:3072
	ds_read_b128 v[158:161], v251 offset:3584
	ds_read_b128 v[178:181], v251 offset:64
	ds_read_b128 v[194:197], v251 offset:576
	ds_read_b128 v[182:185], v251 offset:1088
	ds_read_b128 v[198:201], v251 offset:1600
	ds_read_b128 v[186:189], v251 offset:2112
	ds_read_b128 v[202:205], v251 offset:2624
	ds_read_b128 v[190:193], v251 offset:3136
	ds_read_b128 v[206:209], v251 offset:3648
	s_lshl_b32 s39, s20, 2
	s_add_i32 s39, s39, s55
	s_mov_b32 s96, 0x2c000
	s_mov_b32 s97, 0
	s_mov_b32 s48, 0xbfb8aa3b
	v_mov_b32_e32 v211, 0
	v_mov_b32_e32 v213, 0
	v_mov_b32_e32 v215, 0
	v_mov_b32_e32 v217, 0
	v_mov_b32_e32 v219, 0
	v_lshlrev_b32_e32 v243, 2, v176
	v_lshlrev_b32_e32 v244, 1, v176
	v_mul_u32_u24_e32 v210, 0x2c00, v1
	v_add_u32_e32 v210, v210, v244
	v_mul_u32_u24_e32 v212, 0xb000, v1
	v_add_u32_e32 v212, v212, v243
	v_add_u32_e32 v214, 0x5800, v212
	v_mul_i32_i24_e32 v216, 0xb000, v237
	v_add_u32_e32 v216, v216, v243
	v_add_u32_e32 v218, 0x5800, v216
	s_waitcnt lgkmcnt(8)
	s_add_i32 s84, s39, 0
	s_mul_i32 s85, s84, 0xb0000
	s_add_u32 s94, s22, s85
	s_addc_u32 s95, s23, 0
	v_lshl_add_u64 v[220:221], s[94:95], 0, v[210:211]
	s_mul_i32 s85, s84, 0x16000
	s_add_u32 s94, s24, s85
	s_addc_u32 s95, s25, 0
	v_lshl_add_u64 v[222:223], s[94:95], 0, v[212:213]
	v_lshl_add_u64 v[246:247], s[94:95], 0, v[214:215]
	s_and_saveexec_b64 s[46:47], s[4:5]
	global_store_dwordx4 v[222:223], v[126:129], off
	global_store_dwordx4 v[246:247], v[110:113], off
	s_or_b64 exec, exec, s[46:47]
	v_pk_fma_f32 v[224:225], v[126:127], v[138:139], v[142:143]
	v_pk_fma_f32 v[226:227], v[128:129], v[140:141], v[144:145]
	v_pk_fma_f32 v[228:229], v[110:111], v[154:155], v[158:159]
	v_pk_fma_f32 v[230:231], v[112:113], v[156:157], v[160:161]
	v_fmac_f32_dpp v224, v126, v134 row_shr:1 row_mask:0xf bank_mask:0xf bound_ctrl:1
	v_fmac_f32_dpp v225, v127, v135 row_shr:1 row_mask:0xf bank_mask:0xf bound_ctrl:1
	v_fmac_f32_dpp v226, v128, v136 row_shr:1 row_mask:0xf bank_mask:0xf bound_ctrl:1
	v_fmac_f32_dpp v227, v129, v137 row_shr:1 row_mask:0xf bank_mask:0xf bound_ctrl:1
	v_fmac_f32_dpp v228, v110, v150 row_shr:1 row_mask:0xf bank_mask:0xf bound_ctrl:1
	v_fmac_f32_dpp v229, v111, v151 row_shr:1 row_mask:0xf bank_mask:0xf bound_ctrl:1
	v_fmac_f32_dpp v230, v112, v152 row_shr:1 row_mask:0xf bank_mask:0xf bound_ctrl:1
	v_fmac_f32_dpp v231, v113, v153 row_shr:1 row_mask:0xf bank_mask:0xf bound_ctrl:1
	v_fmac_f32_dpp v224, v126, v130 row_shr:2 row_mask:0xf bank_mask:0xf bound_ctrl:1
	v_fmac_f32_dpp v225, v127, v131 row_shr:2 row_mask:0xf bank_mask:0xf bound_ctrl:1
	v_fmac_f32_dpp v226, v128, v132 row_shr:2 row_mask:0xf bank_mask:0xf bound_ctrl:1
	v_fmac_f32_dpp v227, v129, v133 row_shr:2 row_mask:0xf bank_mask:0xf bound_ctrl:1
	v_fmac_f32_dpp v228, v110, v146 row_shr:2 row_mask:0xf bank_mask:0xf bound_ctrl:1
	v_fmac_f32_dpp v229, v111, v147 row_shr:2 row_mask:0xf bank_mask:0xf bound_ctrl:1
	v_fmac_f32_dpp v230, v112, v148 row_shr:2 row_mask:0xf bank_mask:0xf bound_ctrl:1
	v_fmac_f32_dpp v231, v113, v149 row_shr:2 row_mask:0xf bank_mask:0xf bound_ctrl:1
	v_pk_mul_f32 v[232:233], v[224:225], s[48:49] op_sel_hi:[1,0]
	v_pk_mul_f32 v[234:235], v[226:227], s[48:49] op_sel_hi:[1,0]
	v_exp_f32_e32 v232, v232
	v_exp_f32_e32 v233, v233
	v_exp_f32_e32 v234, v234
	v_exp_f32_e32 v235, v235
	v_pk_add_f32 v[232:233], v[232:233], 1.0 op_sel_hi:[1,0]
	v_pk_add_f32 v[234:235], v[234:235], 1.0 op_sel_hi:[1,0]
	v_rcp_f32_e32 v232, v232
	v_rcp_f32_e32 v233, v233
	v_rcp_f32_e32 v234, v234
	v_rcp_f32_e32 v235, v235
	v_pk_mul_f32 v[224:225], v[224:225], v[232:233]
	v_pk_mul_f32 v[226:227], v[226:227], v[234:235]
	v_pk_mul_f32 v[224:225], v[224:225], v[228:229]
	v_pk_mul_f32 v[226:227], v[226:227], v[230:231]
	v_cvt_pk_bf16_f32 v168, v224, v225
	v_cvt_pk_bf16_f32 v169, v226, v227
	s_and_saveexec_b64 s[46:47], s[8:9]
	global_store_dwordx2 v[220:221], v[168:169], off
	s_or_b64 exec, exec, s[46:47]
	v_pk_fma_f32 v[224:225], v[118:119], v[138:139], v[142:143]
	v_pk_fma_f32 v[226:227], v[120:121], v[140:141], v[144:145]
	v_pk_fma_f32 v[228:229], v[94:95], v[154:155], v[158:159]
	v_pk_fma_f32 v[230:231], v[96:97], v[156:157], v[160:161]
	v_fmac_f32_dpp v224, v118, v134 row_shr:1 row_mask:0xf bank_mask:0xf bound_ctrl:1
	v_fmac_f32_dpp v225, v119, v135 row_shr:1 row_mask:0xf bank_mask:0xf bound_ctrl:1
	v_fmac_f32_dpp v226, v120, v136 row_shr:1 row_mask:0xf bank_mask:0xf bound_ctrl:1
	v_fmac_f32_dpp v227, v121, v137 row_shr:1 row_mask:0xf bank_mask:0xf bound_ctrl:1
	v_fmac_f32_dpp v228, v94, v150 row_shr:1 row_mask:0xf bank_mask:0xf bound_ctrl:1
	v_fmac_f32_dpp v229, v95, v151 row_shr:1 row_mask:0xf bank_mask:0xf bound_ctrl:1
	v_fmac_f32_dpp v230, v96, v152 row_shr:1 row_mask:0xf bank_mask:0xf bound_ctrl:1
	v_fmac_f32_dpp v231, v97, v153 row_shr:1 row_mask:0xf bank_mask:0xf bound_ctrl:1
	v_fmac_f32_dpp v224, v118, v130 row_shr:2 row_mask:0xf bank_mask:0xf bound_ctrl:1
	v_fmac_f32_dpp v225, v119, v131 row_shr:2 row_mask:0xf bank_mask:0xf bound_ctrl:1
	v_fmac_f32_dpp v226, v120, v132 row_shr:2 row_mask:0xf bank_mask:0xf bound_ctrl:1
	v_fmac_f32_dpp v227, v121, v133 row_shr:2 row_mask:0xf bank_mask:0xf bound_ctrl:1
	v_fmac_f32_dpp v228, v94, v146 row_shr:2 row_mask:0xf bank_mask:0xf bound_ctrl:1
	v_fmac_f32_dpp v229, v95, v147 row_shr:2 row_mask:0xf bank_mask:0xf bound_ctrl:1
	v_fmac_f32_dpp v230, v96, v148 row_shr:2 row_mask:0xf bank_mask:0xf bound_ctrl:1
	v_fmac_f32_dpp v231, v97, v149 row_shr:2 row_mask:0xf bank_mask:0xf bound_ctrl:1
	v_fmac_f32_dpp v224, v126, v134 row_shl:15 row_mask:0xf bank_mask:0xf bound_ctrl:1
	v_fmac_f32_dpp v225, v127, v135 row_shl:15 row_mask:0xf bank_mask:0xf bound_ctrl:1
	v_fmac_f32_dpp v226, v128, v136 row_shl:15 row_mask:0xf bank_mask:0xf bound_ctrl:1
	v_fmac_f32_dpp v227, v129, v137 row_shl:15 row_mask:0xf bank_mask:0xf bound_ctrl:1
	v_fmac_f32_dpp v228, v110, v150 row_shl:15 row_mask:0xf bank_mask:0xf bound_ctrl:1
	v_fmac_f32_dpp v229, v111, v151 row_shl:15 row_mask:0xf bank_mask:0xf bound_ctrl:1
	v_fmac_f32_dpp v230, v112, v152 row_shl:15 row_mask:0xf bank_mask:0xf bound_ctrl:1
	v_fmac_f32_dpp v231, v113, v153 row_shl:15 row_mask:0xf bank_mask:0xf bound_ctrl:1
	v_fmac_f32_dpp v224, v126, v130 row_shl:14 row_mask:0xf bank_mask:0xf bound_ctrl:1
	v_fmac_f32_dpp v225, v127, v131 row_shl:14 row_mask:0xf bank_mask:0xf bound_ctrl:1
	v_fmac_f32_dpp v226, v128, v132 row_shl:14 row_mask:0xf bank_mask:0xf bound_ctrl:1
	v_fmac_f32_dpp v227, v129, v133 row_shl:14 row_mask:0xf bank_mask:0xf bound_ctrl:1
	v_fmac_f32_dpp v228, v110, v146 row_shl:14 row_mask:0xf bank_mask:0xf bound_ctrl:1
	v_fmac_f32_dpp v229, v111, v147 row_shl:14 row_mask:0xf bank_mask:0xf bound_ctrl:1
	v_fmac_f32_dpp v230, v112, v148 row_shl:14 row_mask:0xf bank_mask:0xf bound_ctrl:1
	v_fmac_f32_dpp v231, v113, v149 row_shl:14 row_mask:0xf bank_mask:0xf bound_ctrl:1
	v_pk_mul_f32 v[232:233], v[224:225], s[48:49] op_sel_hi:[1,0]
	v_pk_mul_f32 v[234:235], v[226:227], s[48:49] op_sel_hi:[1,0]
	v_exp_f32_e32 v232, v232
	v_exp_f32_e32 v233, v233
	v_exp_f32_e32 v234, v234
	v_exp_f32_e32 v235, v235
	v_pk_add_f32 v[232:233], v[232:233], 1.0 op_sel_hi:[1,0]
	v_pk_add_f32 v[234:235], v[234:235], 1.0 op_sel_hi:[1,0]
	v_rcp_f32_e32 v232, v232
	v_rcp_f32_e32 v233, v233
	v_rcp_f32_e32 v234, v234
	v_rcp_f32_e32 v235, v235
	v_lshl_add_u64 v[220:221], v[220:221], 0, s[96:97]
	v_pk_mul_f32 v[224:225], v[224:225], v[232:233]
	v_pk_mul_f32 v[226:227], v[226:227], v[234:235]
	v_pk_mul_f32 v[224:225], v[224:225], v[228:229]
	v_pk_mul_f32 v[226:227], v[226:227], v[230:231]
	v_cvt_pk_bf16_f32 v168, v224, v225
	v_cvt_pk_bf16_f32 v169, v226, v227
	global_store_dwordx2 v[220:221], v[168:169], off
	v_pk_fma_f32 v[224:225], v[106:107], v[138:139], v[142:143]
	v_pk_fma_f32 v[226:227], v[108:109], v[140:141], v[144:145]
	v_pk_fma_f32 v[228:229], v[78:79], v[154:155], v[158:159]
	v_pk_fma_f32 v[230:231], v[80:81], v[156:157], v[160:161]
	v_fmac_f32_dpp v224, v106, v134 row_shr:1 row_mask:0xf bank_mask:0xf bound_ctrl:1
	v_fmac_f32_dpp v225, v107, v135 row_shr:1 row_mask:0xf bank_mask:0xf bound_ctrl:1
	v_fmac_f32_dpp v226, v108, v136 row_shr:1 row_mask:0xf bank_mask:0xf bound_ctrl:1
	v_fmac_f32_dpp v227, v109, v137 row_shr:1 row_mask:0xf bank_mask:0xf bound_ctrl:1
	v_fmac_f32_dpp v228, v78, v150 row_shr:1 row_mask:0xf bank_mask:0xf bound_ctrl:1
	v_fmac_f32_dpp v229, v79, v151 row_shr:1 row_mask:0xf bank_mask:0xf bound_ctrl:1
	v_fmac_f32_dpp v230, v80, v152 row_shr:1 row_mask:0xf bank_mask:0xf bound_ctrl:1
	v_fmac_f32_dpp v231, v81, v153 row_shr:1 row_mask:0xf bank_mask:0xf bound_ctrl:1
	v_fmac_f32_dpp v224, v106, v130 row_shr:2 row_mask:0xf bank_mask:0xf bound_ctrl:1
	v_fmac_f32_dpp v225, v107, v131 row_shr:2 row_mask:0xf bank_mask:0xf bound_ctrl:1
	v_fmac_f32_dpp v226, v108, v132 row_shr:2 row_mask:0xf bank_mask:0xf bound_ctrl:1
	v_fmac_f32_dpp v227, v109, v133 row_shr:2 row_mask:0xf bank_mask:0xf bound_ctrl:1
	v_fmac_f32_dpp v228, v78, v146 row_shr:2 row_mask:0xf bank_mask:0xf bound_ctrl:1
	v_fmac_f32_dpp v229, v79, v147 row_shr:2 row_mask:0xf bank_mask:0xf bound_ctrl:1
	v_fmac_f32_dpp v230, v80, v148 row_shr:2 row_mask:0xf bank_mask:0xf bound_ctrl:1
	v_fmac_f32_dpp v231, v81, v149 row_shr:2 row_mask:0xf bank_mask:0xf bound_ctrl:1
	v_fmac_f32_dpp v224, v118, v134 row_shl:15 row_mask:0xf bank_mask:0xf bound_ctrl:1
	v_fmac_f32_dpp v225, v119, v135 row_shl:15 row_mask:0xf bank_mask:0xf bound_ctrl:1
	v_fmac_f32_dpp v226, v120, v136 row_shl:15 row_mask:0xf bank_mask:0xf bound_ctrl:1
	v_fmac_f32_dpp v227, v121, v137 row_shl:15 row_mask:0xf bank_mask:0xf bound_ctrl:1
	v_fmac_f32_dpp v228, v94, v150 row_shl:15 row_mask:0xf bank_mask:0xf bound_ctrl:1
	v_fmac_f32_dpp v229, v95, v151 row_shl:15 row_mask:0xf bank_mask:0xf bound_ctrl:1
	v_fmac_f32_dpp v230, v96, v152 row_shl:15 row_mask:0xf bank_mask:0xf bound_ctrl:1
	v_fmac_f32_dpp v231, v97, v153 row_shl:15 row_mask:0xf bank_mask:0xf bound_ctrl:1
	v_fmac_f32_dpp v224, v118, v130 row_shl:14 row_mask:0xf bank_mask:0xf bound_ctrl:1
	v_fmac_f32_dpp v225, v119, v131 row_shl:14 row_mask:0xf bank_mask:0xf bound_ctrl:1
	v_fmac_f32_dpp v226, v120, v132 row_shl:14 row_mask:0xf bank_mask:0xf bound_ctrl:1
	v_fmac_f32_dpp v227, v121, v133 row_shl:14 row_mask:0xf bank_mask:0xf bound_ctrl:1
	v_fmac_f32_dpp v228, v94, v146 row_shl:14 row_mask:0xf bank_mask:0xf bound_ctrl:1
	v_fmac_f32_dpp v229, v95, v147 row_shl:14 row_mask:0xf bank_mask:0xf bound_ctrl:1
	v_fmac_f32_dpp v230, v96, v148 row_shl:14 row_mask:0xf bank_mask:0xf bound_ctrl:1
	v_fmac_f32_dpp v231, v97, v149 row_shl:14 row_mask:0xf bank_mask:0xf bound_ctrl:1
	v_pk_mul_f32 v[232:233], v[224:225], s[48:49] op_sel_hi:[1,0]
	v_pk_mul_f32 v[234:235], v[226:227], s[48:49] op_sel_hi:[1,0]
	v_exp_f32_e32 v232, v232
	v_exp_f32_e32 v233, v233
	v_exp_f32_e32 v234, v234
	v_exp_f32_e32 v235, v235
	v_pk_add_f32 v[232:233], v[232:233], 1.0 op_sel_hi:[1,0]
	v_pk_add_f32 v[234:235], v[234:235], 1.0 op_sel_hi:[1,0]
	v_rcp_f32_e32 v232, v232
	v_rcp_f32_e32 v233, v233
	v_rcp_f32_e32 v234, v234
	v_rcp_f32_e32 v235, v235
	v_lshl_add_u64 v[220:221], v[220:221], 0, s[96:97]
	v_pk_mul_f32 v[224:225], v[224:225], v[232:233]
	v_pk_mul_f32 v[226:227], v[226:227], v[234:235]
	v_pk_mul_f32 v[224:225], v[224:225], v[228:229]
	v_pk_mul_f32 v[226:227], v[226:227], v[230:231]
	v_cvt_pk_bf16_f32 v168, v224, v225
	v_cvt_pk_bf16_f32 v169, v226, v227
	global_store_dwordx2 v[220:221], v[168:169], off
	s_add_u32 s94, s26, s85
	s_addc_u32 s95, s27, 0
	v_lshl_add_u64 v[222:223], s[94:95], 0, v[216:217]
	v_lshl_add_u64 v[246:247], s[94:95], 0, v[218:219]
	s_and_saveexec_b64 s[46:47], s[6:7]
	global_store_dwordx4 v[222:223], v[90:93], off
	global_store_dwordx4 v[246:247], v[70:73], off
	s_or_b64 exec, exec, s[46:47]
	v_pk_fma_f32 v[224:225], v[90:91], v[138:139], v[142:143]
	v_pk_fma_f32 v[226:227], v[92:93], v[140:141], v[144:145]
	v_pk_fma_f32 v[228:229], v[70:71], v[154:155], v[158:159]
	v_pk_fma_f32 v[230:231], v[72:73], v[156:157], v[160:161]
	v_fmac_f32_dpp v224, v90, v134 row_shr:1 row_mask:0xf bank_mask:0xf bound_ctrl:1
	v_fmac_f32_dpp v225, v91, v135 row_shr:1 row_mask:0xf bank_mask:0xf bound_ctrl:1
	v_fmac_f32_dpp v226, v92, v136 row_shr:1 row_mask:0xf bank_mask:0xf bound_ctrl:1
	v_fmac_f32_dpp v227, v93, v137 row_shr:1 row_mask:0xf bank_mask:0xf bound_ctrl:1
	v_fmac_f32_dpp v228, v70, v150 row_shr:1 row_mask:0xf bank_mask:0xf bound_ctrl:1
	v_fmac_f32_dpp v229, v71, v151 row_shr:1 row_mask:0xf bank_mask:0xf bound_ctrl:1
	v_fmac_f32_dpp v230, v72, v152 row_shr:1 row_mask:0xf bank_mask:0xf bound_ctrl:1
	v_fmac_f32_dpp v231, v73, v153 row_shr:1 row_mask:0xf bank_mask:0xf bound_ctrl:1
	v_fmac_f32_dpp v224, v90, v130 row_shr:2 row_mask:0xf bank_mask:0xf bound_ctrl:1
	v_fmac_f32_dpp v225, v91, v131 row_shr:2 row_mask:0xf bank_mask:0xf bound_ctrl:1
	v_fmac_f32_dpp v226, v92, v132 row_shr:2 row_mask:0xf bank_mask:0xf bound_ctrl:1
	v_fmac_f32_dpp v227, v93, v133 row_shr:2 row_mask:0xf bank_mask:0xf bound_ctrl:1
	v_fmac_f32_dpp v228, v70, v146 row_shr:2 row_mask:0xf bank_mask:0xf bound_ctrl:1
	v_fmac_f32_dpp v229, v71, v147 row_shr:2 row_mask:0xf bank_mask:0xf bound_ctrl:1
	v_fmac_f32_dpp v230, v72, v148 row_shr:2 row_mask:0xf bank_mask:0xf bound_ctrl:1
	v_fmac_f32_dpp v231, v73, v149 row_shr:2 row_mask:0xf bank_mask:0xf bound_ctrl:1
	v_fmac_f32_dpp v224, v106, v134 row_shl:15 row_mask:0xf bank_mask:0xf bound_ctrl:1
	v_fmac_f32_dpp v225, v107, v135 row_shl:15 row_mask:0xf bank_mask:0xf bound_ctrl:1
	v_fmac_f32_dpp v226, v108, v136 row_shl:15 row_mask:0xf bank_mask:0xf bound_ctrl:1
	v_fmac_f32_dpp v227, v109, v137 row_shl:15 row_mask:0xf bank_mask:0xf bound_ctrl:1
	v_fmac_f32_dpp v228, v78, v150 row_shl:15 row_mask:0xf bank_mask:0xf bound_ctrl:1
	v_fmac_f32_dpp v229, v79, v151 row_shl:15 row_mask:0xf bank_mask:0xf bound_ctrl:1
	v_fmac_f32_dpp v230, v80, v152 row_shl:15 row_mask:0xf bank_mask:0xf bound_ctrl:1
	v_fmac_f32_dpp v231, v81, v153 row_shl:15 row_mask:0xf bank_mask:0xf bound_ctrl:1
	v_fmac_f32_dpp v224, v106, v130 row_shl:14 row_mask:0xf bank_mask:0xf bound_ctrl:1
	v_fmac_f32_dpp v225, v107, v131 row_shl:14 row_mask:0xf bank_mask:0xf bound_ctrl:1
	v_fmac_f32_dpp v226, v108, v132 row_shl:14 row_mask:0xf bank_mask:0xf bound_ctrl:1
	v_fmac_f32_dpp v227, v109, v133 row_shl:14 row_mask:0xf bank_mask:0xf bound_ctrl:1
	v_fmac_f32_dpp v228, v78, v146 row_shl:14 row_mask:0xf bank_mask:0xf bound_ctrl:1
	v_fmac_f32_dpp v229, v79, v147 row_shl:14 row_mask:0xf bank_mask:0xf bound_ctrl:1
	v_fmac_f32_dpp v230, v80, v148 row_shl:14 row_mask:0xf bank_mask:0xf bound_ctrl:1
	v_fmac_f32_dpp v231, v81, v149 row_shl:14 row_mask:0xf bank_mask:0xf bound_ctrl:1
	v_pk_mul_f32 v[232:233], v[224:225], s[48:49] op_sel_hi:[1,0]
	v_pk_mul_f32 v[234:235], v[226:227], s[48:49] op_sel_hi:[1,0]
	v_exp_f32_e32 v232, v232
	v_exp_f32_e32 v233, v233
	v_exp_f32_e32 v234, v234
	v_exp_f32_e32 v235, v235
	v_pk_add_f32 v[232:233], v[232:233], 1.0 op_sel_hi:[1,0]
	v_pk_add_f32 v[234:235], v[234:235], 1.0 op_sel_hi:[1,0]
	v_rcp_f32_e32 v232, v232
	v_rcp_f32_e32 v233, v233
	v_rcp_f32_e32 v234, v234
	v_rcp_f32_e32 v235, v235
	v_lshl_add_u64 v[220:221], v[220:221], 0, s[96:97]
	v_pk_mul_f32 v[224:225], v[224:225], v[232:233]
	v_pk_mul_f32 v[226:227], v[226:227], v[234:235]
	v_pk_mul_f32 v[224:225], v[224:225], v[228:229]
	v_pk_mul_f32 v[226:227], v[226:227], v[230:231]
	v_cvt_pk_bf16_f32 v168, v224, v225
	v_cvt_pk_bf16_f32 v169, v226, v227
	global_store_dwordx2 v[220:221], v[168:169], off
	s_add_i32 s84, s39, 2
	s_mul_i32 s85, s84, 0xb0000
	s_add_u32 s94, s22, s85
	s_addc_u32 s95, s23, 0
	v_lshl_add_u64 v[220:221], s[94:95], 0, v[210:211]
	s_mul_i32 s85, s84, 0x16000
	s_add_u32 s94, s24, s85
	s_addc_u32 s95, s25, 0
	v_lshl_add_u64 v[222:223], s[94:95], 0, v[212:213]
	v_lshl_add_u64 v[246:247], s[94:95], 0, v[214:215]
	s_and_saveexec_b64 s[46:47], s[4:5]
	global_store_dwordx4 v[222:223], v[62:65], off
	global_store_dwordx4 v[246:247], v[46:49], off
	s_or_b64 exec, exec, s[46:47]
	v_pk_fma_f32 v[224:225], v[62:63], v[138:139], v[142:143]
	v_pk_fma_f32 v[226:227], v[64:65], v[140:141], v[144:145]
	v_pk_fma_f32 v[228:229], v[46:47], v[154:155], v[158:159]
	v_pk_fma_f32 v[230:231], v[48:49], v[156:157], v[160:161]
	v_fmac_f32_dpp v224, v62, v134 row_shr:1 row_mask:0xf bank_mask:0xf bound_ctrl:1
	v_fmac_f32_dpp v225, v63, v135 row_shr:1 row_mask:0xf bank_mask:0xf bound_ctrl:1
	v_fmac_f32_dpp v226, v64, v136 row_shr:1 row_mask:0xf bank_mask:0xf bound_ctrl:1
	v_fmac_f32_dpp v227, v65, v137 row_shr:1 row_mask:0xf bank_mask:0xf bound_ctrl:1
	v_fmac_f32_dpp v228, v46, v150 row_shr:1 row_mask:0xf bank_mask:0xf bound_ctrl:1
	v_fmac_f32_dpp v229, v47, v151 row_shr:1 row_mask:0xf bank_mask:0xf bound_ctrl:1
	v_fmac_f32_dpp v230, v48, v152 row_shr:1 row_mask:0xf bank_mask:0xf bound_ctrl:1
	v_fmac_f32_dpp v231, v49, v153 row_shr:1 row_mask:0xf bank_mask:0xf bound_ctrl:1
	v_fmac_f32_dpp v224, v62, v130 row_shr:2 row_mask:0xf bank_mask:0xf bound_ctrl:1
	v_fmac_f32_dpp v225, v63, v131 row_shr:2 row_mask:0xf bank_mask:0xf bound_ctrl:1
	v_fmac_f32_dpp v226, v64, v132 row_shr:2 row_mask:0xf bank_mask:0xf bound_ctrl:1
	v_fmac_f32_dpp v227, v65, v133 row_shr:2 row_mask:0xf bank_mask:0xf bound_ctrl:1
	v_fmac_f32_dpp v228, v46, v146 row_shr:2 row_mask:0xf bank_mask:0xf bound_ctrl:1
	v_fmac_f32_dpp v229, v47, v147 row_shr:2 row_mask:0xf bank_mask:0xf bound_ctrl:1
	v_fmac_f32_dpp v230, v48, v148 row_shr:2 row_mask:0xf bank_mask:0xf bound_ctrl:1
	v_fmac_f32_dpp v231, v49, v149 row_shr:2 row_mask:0xf bank_mask:0xf bound_ctrl:1
	v_pk_mul_f32 v[232:233], v[224:225], s[48:49] op_sel_hi:[1,0]
	v_pk_mul_f32 v[234:235], v[226:227], s[48:49] op_sel_hi:[1,0]
	v_exp_f32_e32 v232, v232
	v_exp_f32_e32 v233, v233
	v_exp_f32_e32 v234, v234
	v_exp_f32_e32 v235, v235
	v_pk_add_f32 v[232:233], v[232:233], 1.0 op_sel_hi:[1,0]
	v_pk_add_f32 v[234:235], v[234:235], 1.0 op_sel_hi:[1,0]
	v_rcp_f32_e32 v232, v232
	v_rcp_f32_e32 v233, v233
	v_rcp_f32_e32 v234, v234
	v_rcp_f32_e32 v235, v235
	v_pk_mul_f32 v[224:225], v[224:225], v[232:233]
	v_pk_mul_f32 v[226:227], v[226:227], v[234:235]
	v_pk_mul_f32 v[224:225], v[224:225], v[228:229]
	v_pk_mul_f32 v[226:227], v[226:227], v[230:231]
	v_cvt_pk_bf16_f32 v168, v224, v225
	v_cvt_pk_bf16_f32 v169, v226, v227
	s_and_saveexec_b64 s[46:47], s[8:9]
	global_store_dwordx2 v[220:221], v[168:169], off
	s_or_b64 exec, exec, s[46:47]
	v_pk_fma_f32 v[224:225], v[54:55], v[138:139], v[142:143]
	v_pk_fma_f32 v[226:227], v[56:57], v[140:141], v[144:145]
	v_pk_fma_f32 v[228:229], v[30:31], v[154:155], v[158:159]
	v_pk_fma_f32 v[230:231], v[32:33], v[156:157], v[160:161]
	v_fmac_f32_dpp v224, v54, v134 row_shr:1 row_mask:0xf bank_mask:0xf bound_ctrl:1
	v_fmac_f32_dpp v225, v55, v135 row_shr:1 row_mask:0xf bank_mask:0xf bound_ctrl:1
	v_fmac_f32_dpp v226, v56, v136 row_shr:1 row_mask:0xf bank_mask:0xf bound_ctrl:1
	v_fmac_f32_dpp v227, v57, v137 row_shr:1 row_mask:0xf bank_mask:0xf bound_ctrl:1
	v_fmac_f32_dpp v228, v30, v150 row_shr:1 row_mask:0xf bank_mask:0xf bound_ctrl:1
	v_fmac_f32_dpp v229, v31, v151 row_shr:1 row_mask:0xf bank_mask:0xf bound_ctrl:1
	v_fmac_f32_dpp v230, v32, v152 row_shr:1 row_mask:0xf bank_mask:0xf bound_ctrl:1
	v_fmac_f32_dpp v231, v33, v153 row_shr:1 row_mask:0xf bank_mask:0xf bound_ctrl:1
	v_fmac_f32_dpp v224, v54, v130 row_shr:2 row_mask:0xf bank_mask:0xf bound_ctrl:1
	v_fmac_f32_dpp v225, v55, v131 row_shr:2 row_mask:0xf bank_mask:0xf bound_ctrl:1
	v_fmac_f32_dpp v226, v56, v132 row_shr:2 row_mask:0xf bank_mask:0xf bound_ctrl:1
	v_fmac_f32_dpp v227, v57, v133 row_shr:2 row_mask:0xf bank_mask:0xf bound_ctrl:1
	v_fmac_f32_dpp v228, v30, v146 row_shr:2 row_mask:0xf bank_mask:0xf bound_ctrl:1
	v_fmac_f32_dpp v229, v31, v147 row_shr:2 row_mask:0xf bank_mask:0xf bound_ctrl:1
	v_fmac_f32_dpp v230, v32, v148 row_shr:2 row_mask:0xf bank_mask:0xf bound_ctrl:1
	v_fmac_f32_dpp v231, v33, v149 row_shr:2 row_mask:0xf bank_mask:0xf bound_ctrl:1
	v_fmac_f32_dpp v224, v62, v134 row_shl:15 row_mask:0xf bank_mask:0xf bound_ctrl:1
	v_fmac_f32_dpp v225, v63, v135 row_shl:15 row_mask:0xf bank_mask:0xf bound_ctrl:1
	v_fmac_f32_dpp v226, v64, v136 row_shl:15 row_mask:0xf bank_mask:0xf bound_ctrl:1
	v_fmac_f32_dpp v227, v65, v137 row_shl:15 row_mask:0xf bank_mask:0xf bound_ctrl:1
	v_fmac_f32_dpp v228, v46, v150 row_shl:15 row_mask:0xf bank_mask:0xf bound_ctrl:1
	v_fmac_f32_dpp v229, v47, v151 row_shl:15 row_mask:0xf bank_mask:0xf bound_ctrl:1
	v_fmac_f32_dpp v230, v48, v152 row_shl:15 row_mask:0xf bank_mask:0xf bound_ctrl:1
	v_fmac_f32_dpp v231, v49, v153 row_shl:15 row_mask:0xf bank_mask:0xf bound_ctrl:1
	v_fmac_f32_dpp v224, v62, v130 row_shl:14 row_mask:0xf bank_mask:0xf bound_ctrl:1
	v_fmac_f32_dpp v225, v63, v131 row_shl:14 row_mask:0xf bank_mask:0xf bound_ctrl:1
	v_fmac_f32_dpp v226, v64, v132 row_shl:14 row_mask:0xf bank_mask:0xf bound_ctrl:1
	v_fmac_f32_dpp v227, v65, v133 row_shl:14 row_mask:0xf bank_mask:0xf bound_ctrl:1
	v_fmac_f32_dpp v228, v46, v146 row_shl:14 row_mask:0xf bank_mask:0xf bound_ctrl:1
	v_fmac_f32_dpp v229, v47, v147 row_shl:14 row_mask:0xf bank_mask:0xf bound_ctrl:1
	v_fmac_f32_dpp v230, v48, v148 row_shl:14 row_mask:0xf bank_mask:0xf bound_ctrl:1
	v_fmac_f32_dpp v231, v49, v149 row_shl:14 row_mask:0xf bank_mask:0xf bound_ctrl:1
	v_pk_mul_f32 v[232:233], v[224:225], s[48:49] op_sel_hi:[1,0]
	v_pk_mul_f32 v[234:235], v[226:227], s[48:49] op_sel_hi:[1,0]
	v_exp_f32_e32 v232, v232
	v_exp_f32_e32 v233, v233
	v_exp_f32_e32 v234, v234
	v_exp_f32_e32 v235, v235
	v_pk_add_f32 v[232:233], v[232:233], 1.0 op_sel_hi:[1,0]
	v_pk_add_f32 v[234:235], v[234:235], 1.0 op_sel_hi:[1,0]
	v_rcp_f32_e32 v232, v232
	v_rcp_f32_e32 v233, v233
	v_rcp_f32_e32 v234, v234
	v_rcp_f32_e32 v235, v235
	v_lshl_add_u64 v[220:221], v[220:221], 0, s[96:97]
	v_pk_mul_f32 v[224:225], v[224:225], v[232:233]
	v_pk_mul_f32 v[226:227], v[226:227], v[234:235]
	v_pk_mul_f32 v[224:225], v[224:225], v[228:229]
	v_pk_mul_f32 v[226:227], v[226:227], v[230:231]
	v_cvt_pk_bf16_f32 v168, v224, v225
	v_cvt_pk_bf16_f32 v169, v226, v227
	global_store_dwordx2 v[220:221], v[168:169], off
	v_pk_fma_f32 v[224:225], v[42:43], v[138:139], v[142:143]
	v_pk_fma_f32 v[226:227], v[44:45], v[140:141], v[144:145]
	v_pk_fma_f32 v[228:229], v[14:15], v[154:155], v[158:159]
	v_pk_fma_f32 v[230:231], v[16:17], v[156:157], v[160:161]
	v_fmac_f32_dpp v224, v42, v134 row_shr:1 row_mask:0xf bank_mask:0xf bound_ctrl:1
	v_fmac_f32_dpp v225, v43, v135 row_shr:1 row_mask:0xf bank_mask:0xf bound_ctrl:1
	v_fmac_f32_dpp v226, v44, v136 row_shr:1 row_mask:0xf bank_mask:0xf bound_ctrl:1
	v_fmac_f32_dpp v227, v45, v137 row_shr:1 row_mask:0xf bank_mask:0xf bound_ctrl:1
	v_fmac_f32_dpp v228, v14, v150 row_shr:1 row_mask:0xf bank_mask:0xf bound_ctrl:1
	v_fmac_f32_dpp v229, v15, v151 row_shr:1 row_mask:0xf bank_mask:0xf bound_ctrl:1
	v_fmac_f32_dpp v230, v16, v152 row_shr:1 row_mask:0xf bank_mask:0xf bound_ctrl:1
	v_fmac_f32_dpp v231, v17, v153 row_shr:1 row_mask:0xf bank_mask:0xf bound_ctrl:1
	v_fmac_f32_dpp v224, v42, v130 row_shr:2 row_mask:0xf bank_mask:0xf bound_ctrl:1
	v_fmac_f32_dpp v225, v43, v131 row_shr:2 row_mask:0xf bank_mask:0xf bound_ctrl:1
	v_fmac_f32_dpp v226, v44, v132 row_shr:2 row_mask:0xf bank_mask:0xf bound_ctrl:1
	v_fmac_f32_dpp v227, v45, v133 row_shr:2 row_mask:0xf bank_mask:0xf bound_ctrl:1
	v_fmac_f32_dpp v228, v14, v146 row_shr:2 row_mask:0xf bank_mask:0xf bound_ctrl:1
	v_fmac_f32_dpp v229, v15, v147 row_shr:2 row_mask:0xf bank_mask:0xf bound_ctrl:1
	v_fmac_f32_dpp v230, v16, v148 row_shr:2 row_mask:0xf bank_mask:0xf bound_ctrl:1
	v_fmac_f32_dpp v231, v17, v149 row_shr:2 row_mask:0xf bank_mask:0xf bound_ctrl:1
	v_fmac_f32_dpp v224, v54, v134 row_shl:15 row_mask:0xf bank_mask:0xf bound_ctrl:1
	v_fmac_f32_dpp v225, v55, v135 row_shl:15 row_mask:0xf bank_mask:0xf bound_ctrl:1
	v_fmac_f32_dpp v226, v56, v136 row_shl:15 row_mask:0xf bank_mask:0xf bound_ctrl:1
	v_fmac_f32_dpp v227, v57, v137 row_shl:15 row_mask:0xf bank_mask:0xf bound_ctrl:1
	v_fmac_f32_dpp v228, v30, v150 row_shl:15 row_mask:0xf bank_mask:0xf bound_ctrl:1
	v_fmac_f32_dpp v229, v31, v151 row_shl:15 row_mask:0xf bank_mask:0xf bound_ctrl:1
	v_fmac_f32_dpp v230, v32, v152 row_shl:15 row_mask:0xf bank_mask:0xf bound_ctrl:1
	v_fmac_f32_dpp v231, v33, v153 row_shl:15 row_mask:0xf bank_mask:0xf bound_ctrl:1
	v_fmac_f32_dpp v224, v54, v130 row_shl:14 row_mask:0xf bank_mask:0xf bound_ctrl:1
	v_fmac_f32_dpp v225, v55, v131 row_shl:14 row_mask:0xf bank_mask:0xf bound_ctrl:1
	v_fmac_f32_dpp v226, v56, v132 row_shl:14 row_mask:0xf bank_mask:0xf bound_ctrl:1
	v_fmac_f32_dpp v227, v57, v133 row_shl:14 row_mask:0xf bank_mask:0xf bound_ctrl:1
	v_fmac_f32_dpp v228, v30, v146 row_shl:14 row_mask:0xf bank_mask:0xf bound_ctrl:1
	v_fmac_f32_dpp v229, v31, v147 row_shl:14 row_mask:0xf bank_mask:0xf bound_ctrl:1
	v_fmac_f32_dpp v230, v32, v148 row_shl:14 row_mask:0xf bank_mask:0xf bound_ctrl:1
	v_fmac_f32_dpp v231, v33, v149 row_shl:14 row_mask:0xf bank_mask:0xf bound_ctrl:1
	v_pk_mul_f32 v[232:233], v[224:225], s[48:49] op_sel_hi:[1,0]
	v_pk_mul_f32 v[234:235], v[226:227], s[48:49] op_sel_hi:[1,0]
	v_exp_f32_e32 v232, v232
	v_exp_f32_e32 v233, v233
	v_exp_f32_e32 v234, v234
	v_exp_f32_e32 v235, v235
	v_pk_add_f32 v[232:233], v[232:233], 1.0 op_sel_hi:[1,0]
	v_pk_add_f32 v[234:235], v[234:235], 1.0 op_sel_hi:[1,0]
	v_rcp_f32_e32 v232, v232
	v_rcp_f32_e32 v233, v233
	v_rcp_f32_e32 v234, v234
	v_rcp_f32_e32 v235, v235
	v_lshl_add_u64 v[220:221], v[220:221], 0, s[96:97]
	v_pk_mul_f32 v[224:225], v[224:225], v[232:233]
	v_pk_mul_f32 v[226:227], v[226:227], v[234:235]
	v_pk_mul_f32 v[224:225], v[224:225], v[228:229]
	v_pk_mul_f32 v[226:227], v[226:227], v[230:231]
	v_cvt_pk_bf16_f32 v168, v224, v225
	v_cvt_pk_bf16_f32 v169, v226, v227
	global_store_dwordx2 v[220:221], v[168:169], off
	s_add_u32 s94, s26, s85
	s_addc_u32 s95, s27, 0
	v_lshl_add_u64 v[222:223], s[94:95], 0, v[216:217]
	v_lshl_add_u64 v[246:247], s[94:95], 0, v[218:219]
	s_and_saveexec_b64 s[46:47], s[6:7]
	global_store_dwordx4 v[222:223], v[26:29], off
	global_store_dwordx4 v[246:247], v[6:9], off
	s_or_b64 exec, exec, s[46:47]
	v_pk_fma_f32 v[224:225], v[26:27], v[138:139], v[142:143]
	v_pk_fma_f32 v[226:227], v[28:29], v[140:141], v[144:145]
	v_pk_fma_f32 v[228:229], v[6:7], v[154:155], v[158:159]
	v_pk_fma_f32 v[230:231], v[8:9], v[156:157], v[160:161]
	v_fmac_f32_dpp v224, v26, v134 row_shr:1 row_mask:0xf bank_mask:0xf bound_ctrl:1
	v_fmac_f32_dpp v225, v27, v135 row_shr:1 row_mask:0xf bank_mask:0xf bound_ctrl:1
	v_fmac_f32_dpp v226, v28, v136 row_shr:1 row_mask:0xf bank_mask:0xf bound_ctrl:1
	v_fmac_f32_dpp v227, v29, v137 row_shr:1 row_mask:0xf bank_mask:0xf bound_ctrl:1
	v_fmac_f32_dpp v228, v6, v150 row_shr:1 row_mask:0xf bank_mask:0xf bound_ctrl:1
	v_fmac_f32_dpp v229, v7, v151 row_shr:1 row_mask:0xf bank_mask:0xf bound_ctrl:1
	v_fmac_f32_dpp v230, v8, v152 row_shr:1 row_mask:0xf bank_mask:0xf bound_ctrl:1
	v_fmac_f32_dpp v231, v9, v153 row_shr:1 row_mask:0xf bank_mask:0xf bound_ctrl:1
	v_fmac_f32_dpp v224, v26, v130 row_shr:2 row_mask:0xf bank_mask:0xf bound_ctrl:1
	v_fmac_f32_dpp v225, v27, v131 row_shr:2 row_mask:0xf bank_mask:0xf bound_ctrl:1
	v_fmac_f32_dpp v226, v28, v132 row_shr:2 row_mask:0xf bank_mask:0xf bound_ctrl:1
	v_fmac_f32_dpp v227, v29, v133 row_shr:2 row_mask:0xf bank_mask:0xf bound_ctrl:1
	v_fmac_f32_dpp v228, v6, v146 row_shr:2 row_mask:0xf bank_mask:0xf bound_ctrl:1
	v_fmac_f32_dpp v229, v7, v147 row_shr:2 row_mask:0xf bank_mask:0xf bound_ctrl:1
	v_fmac_f32_dpp v230, v8, v148 row_shr:2 row_mask:0xf bank_mask:0xf bound_ctrl:1
	v_fmac_f32_dpp v231, v9, v149 row_shr:2 row_mask:0xf bank_mask:0xf bound_ctrl:1
	v_fmac_f32_dpp v224, v42, v134 row_shl:15 row_mask:0xf bank_mask:0xf bound_ctrl:1
	v_fmac_f32_dpp v225, v43, v135 row_shl:15 row_mask:0xf bank_mask:0xf bound_ctrl:1
	v_fmac_f32_dpp v226, v44, v136 row_shl:15 row_mask:0xf bank_mask:0xf bound_ctrl:1
	v_fmac_f32_dpp v227, v45, v137 row_shl:15 row_mask:0xf bank_mask:0xf bound_ctrl:1
	v_fmac_f32_dpp v228, v14, v150 row_shl:15 row_mask:0xf bank_mask:0xf bound_ctrl:1
	v_fmac_f32_dpp v229, v15, v151 row_shl:15 row_mask:0xf bank_mask:0xf bound_ctrl:1
	v_fmac_f32_dpp v230, v16, v152 row_shl:15 row_mask:0xf bank_mask:0xf bound_ctrl:1
	v_fmac_f32_dpp v231, v17, v153 row_shl:15 row_mask:0xf bank_mask:0xf bound_ctrl:1
	v_fmac_f32_dpp v224, v42, v130 row_shl:14 row_mask:0xf bank_mask:0xf bound_ctrl:1
	v_fmac_f32_dpp v225, v43, v131 row_shl:14 row_mask:0xf bank_mask:0xf bound_ctrl:1
	v_fmac_f32_dpp v226, v44, v132 row_shl:14 row_mask:0xf bank_mask:0xf bound_ctrl:1
	v_fmac_f32_dpp v227, v45, v133 row_shl:14 row_mask:0xf bank_mask:0xf bound_ctrl:1
	v_fmac_f32_dpp v228, v14, v146 row_shl:14 row_mask:0xf bank_mask:0xf bound_ctrl:1
	v_fmac_f32_dpp v229, v15, v147 row_shl:14 row_mask:0xf bank_mask:0xf bound_ctrl:1
	v_fmac_f32_dpp v230, v16, v148 row_shl:14 row_mask:0xf bank_mask:0xf bound_ctrl:1
	v_fmac_f32_dpp v231, v17, v149 row_shl:14 row_mask:0xf bank_mask:0xf bound_ctrl:1
	v_pk_mul_f32 v[232:233], v[224:225], s[48:49] op_sel_hi:[1,0]
	v_pk_mul_f32 v[234:235], v[226:227], s[48:49] op_sel_hi:[1,0]
	v_exp_f32_e32 v232, v232
	v_exp_f32_e32 v233, v233
	v_exp_f32_e32 v234, v234
	v_exp_f32_e32 v235, v235
	v_pk_add_f32 v[232:233], v[232:233], 1.0 op_sel_hi:[1,0]
	v_pk_add_f32 v[234:235], v[234:235], 1.0 op_sel_hi:[1,0]
	v_rcp_f32_e32 v232, v232
	v_rcp_f32_e32 v233, v233
	v_rcp_f32_e32 v234, v234
	v_rcp_f32_e32 v235, v235
	v_lshl_add_u64 v[220:221], v[220:221], 0, s[96:97]
	v_pk_mul_f32 v[224:225], v[224:225], v[232:233]
	v_pk_mul_f32 v[226:227], v[226:227], v[234:235]
	v_pk_mul_f32 v[224:225], v[224:225], v[228:229]
	v_pk_mul_f32 v[226:227], v[226:227], v[230:231]
	v_cvt_pk_bf16_f32 v168, v224, v225
	v_cvt_pk_bf16_f32 v169, v226, v227
	global_store_dwordx2 v[220:221], v[168:169], off
	s_waitcnt lgkmcnt(0)
	ds_read_b128 v[130:133], v240
	ds_read_b128 v[134:137], v240 offset:1024
	ds_read_b128 v[138:141], v240 offset:2048
	ds_read_b128 v[142:145], v240 offset:3072
	ds_read_b128 v[146:149], v241
	ds_read_b128 v[150:153], v241 offset:1024
	ds_read_b128 v[154:157], v241 offset:2048
	ds_read_b128 v[158:161], v241 offset:3072
	s_add_i32 s84, s39, 0
	s_mul_i32 s85, s84, 0xb0000
	s_add_u32 s94, s22, s85
	s_addc_u32 s95, s23, 0
	v_lshl_add_u64 v[220:221], s[94:95], 0, v[210:211]
	s_mul_i32 s85, s84, 0x16000
	s_add_u32 s94, s24, s85
	s_addc_u32 s95, s25, 0
	v_lshl_add_u64 v[222:223], s[94:95], 0, v[212:213]
	v_lshl_add_u64 v[246:247], s[94:95], 0, v[214:215]
	s_and_saveexec_b64 s[46:47], s[4:5]
	global_store_dwordx4 v[222:223], v[122:125], off offset:64
	global_store_dwordx4 v[246:247], v[102:105], off offset:64
	s_or_b64 exec, exec, s[46:47]
	v_pk_fma_f32 v[224:225], v[122:123], v[186:187], v[190:191]
	v_pk_fma_f32 v[226:227], v[124:125], v[188:189], v[192:193]
	v_pk_fma_f32 v[228:229], v[102:103], v[202:203], v[206:207]
	v_pk_fma_f32 v[230:231], v[104:105], v[204:205], v[208:209]
	v_fmac_f32_dpp v224, v122, v182 row_shr:1 row_mask:0xf bank_mask:0xf bound_ctrl:1
	v_fmac_f32_dpp v225, v123, v183 row_shr:1 row_mask:0xf bank_mask:0xf bound_ctrl:1
	v_fmac_f32_dpp v226, v124, v184 row_shr:1 row_mask:0xf bank_mask:0xf bound_ctrl:1
	v_fmac_f32_dpp v227, v125, v185 row_shr:1 row_mask:0xf bank_mask:0xf bound_ctrl:1
	v_fmac_f32_dpp v228, v102, v198 row_shr:1 row_mask:0xf bank_mask:0xf bound_ctrl:1
	v_fmac_f32_dpp v229, v103, v199 row_shr:1 row_mask:0xf bank_mask:0xf bound_ctrl:1
	v_fmac_f32_dpp v230, v104, v200 row_shr:1 row_mask:0xf bank_mask:0xf bound_ctrl:1
	v_fmac_f32_dpp v231, v105, v201 row_shr:1 row_mask:0xf bank_mask:0xf bound_ctrl:1
	v_fmac_f32_dpp v224, v122, v178 row_shr:2 row_mask:0xf bank_mask:0xf bound_ctrl:1
	v_fmac_f32_dpp v225, v123, v179 row_shr:2 row_mask:0xf bank_mask:0xf bound_ctrl:1
	v_fmac_f32_dpp v226, v124, v180 row_shr:2 row_mask:0xf bank_mask:0xf bound_ctrl:1
	v_fmac_f32_dpp v227, v125, v181 row_shr:2 row_mask:0xf bank_mask:0xf bound_ctrl:1
	v_fmac_f32_dpp v228, v102, v194 row_shr:2 row_mask:0xf bank_mask:0xf bound_ctrl:1
	v_fmac_f32_dpp v229, v103, v195 row_shr:2 row_mask:0xf bank_mask:0xf bound_ctrl:1
	v_fmac_f32_dpp v230, v104, v196 row_shr:2 row_mask:0xf bank_mask:0xf bound_ctrl:1
	v_fmac_f32_dpp v231, v105, v197 row_shr:2 row_mask:0xf bank_mask:0xf bound_ctrl:1
	v_pk_mul_f32 v[232:233], v[224:225], s[48:49] op_sel_hi:[1,0]
	v_pk_mul_f32 v[234:235], v[226:227], s[48:49] op_sel_hi:[1,0]
	v_exp_f32_e32 v232, v232
	v_exp_f32_e32 v233, v233
	v_exp_f32_e32 v234, v234
	v_exp_f32_e32 v235, v235
	v_pk_add_f32 v[232:233], v[232:233], 1.0 op_sel_hi:[1,0]
	v_pk_add_f32 v[234:235], v[234:235], 1.0 op_sel_hi:[1,0]
	v_rcp_f32_e32 v232, v232
	v_rcp_f32_e32 v233, v233
	v_rcp_f32_e32 v234, v234
	v_rcp_f32_e32 v235, v235
	v_pk_mul_f32 v[224:225], v[224:225], v[232:233]
	v_pk_mul_f32 v[226:227], v[226:227], v[234:235]
	v_pk_mul_f32 v[224:225], v[224:225], v[228:229]
	v_pk_mul_f32 v[226:227], v[226:227], v[230:231]
	v_cvt_pk_bf16_f32 v168, v224, v225
	v_cvt_pk_bf16_f32 v169, v226, v227
	s_and_saveexec_b64 s[46:47], s[8:9]
	global_store_dwordx2 v[220:221], v[168:169], off offset:32
	s_or_b64 exec, exec, s[46:47]
	v_pk_fma_f32 v[224:225], v[114:115], v[186:187], v[190:191]
	v_pk_fma_f32 v[226:227], v[116:117], v[188:189], v[192:193]
	v_pk_fma_f32 v[228:229], v[86:87], v[202:203], v[206:207]
	v_pk_fma_f32 v[230:231], v[88:89], v[204:205], v[208:209]
	v_fmac_f32_dpp v224, v114, v182 row_shr:1 row_mask:0xf bank_mask:0xf bound_ctrl:1
	v_fmac_f32_dpp v225, v115, v183 row_shr:1 row_mask:0xf bank_mask:0xf bound_ctrl:1
	v_fmac_f32_dpp v226, v116, v184 row_shr:1 row_mask:0xf bank_mask:0xf bound_ctrl:1
	v_fmac_f32_dpp v227, v117, v185 row_shr:1 row_mask:0xf bank_mask:0xf bound_ctrl:1
	v_fmac_f32_dpp v228, v86, v198 row_shr:1 row_mask:0xf bank_mask:0xf bound_ctrl:1
	v_fmac_f32_dpp v229, v87, v199 row_shr:1 row_mask:0xf bank_mask:0xf bound_ctrl:1
	v_fmac_f32_dpp v230, v88, v200 row_shr:1 row_mask:0xf bank_mask:0xf bound_ctrl:1
	v_fmac_f32_dpp v231, v89, v201 row_shr:1 row_mask:0xf bank_mask:0xf bound_ctrl:1
	v_fmac_f32_dpp v224, v114, v178 row_shr:2 row_mask:0xf bank_mask:0xf bound_ctrl:1
	v_fmac_f32_dpp v225, v115, v179 row_shr:2 row_mask:0xf bank_mask:0xf bound_ctrl:1
	v_fmac_f32_dpp v226, v116, v180 row_shr:2 row_mask:0xf bank_mask:0xf bound_ctrl:1
	v_fmac_f32_dpp v227, v117, v181 row_shr:2 row_mask:0xf bank_mask:0xf bound_ctrl:1
	v_fmac_f32_dpp v228, v86, v194 row_shr:2 row_mask:0xf bank_mask:0xf bound_ctrl:1
	v_fmac_f32_dpp v229, v87, v195 row_shr:2 row_mask:0xf bank_mask:0xf bound_ctrl:1
	v_fmac_f32_dpp v230, v88, v196 row_shr:2 row_mask:0xf bank_mask:0xf bound_ctrl:1
	v_fmac_f32_dpp v231, v89, v197 row_shr:2 row_mask:0xf bank_mask:0xf bound_ctrl:1
	v_fmac_f32_dpp v224, v122, v182 row_shl:15 row_mask:0xf bank_mask:0xf bound_ctrl:1
	v_fmac_f32_dpp v225, v123, v183 row_shl:15 row_mask:0xf bank_mask:0xf bound_ctrl:1
	v_fmac_f32_dpp v226, v124, v184 row_shl:15 row_mask:0xf bank_mask:0xf bound_ctrl:1
	v_fmac_f32_dpp v227, v125, v185 row_shl:15 row_mask:0xf bank_mask:0xf bound_ctrl:1
	v_fmac_f32_dpp v228, v102, v198 row_shl:15 row_mask:0xf bank_mask:0xf bound_ctrl:1
	v_fmac_f32_dpp v229, v103, v199 row_shl:15 row_mask:0xf bank_mask:0xf bound_ctrl:1
	v_fmac_f32_dpp v230, v104, v200 row_shl:15 row_mask:0xf bank_mask:0xf bound_ctrl:1
	v_fmac_f32_dpp v231, v105, v201 row_shl:15 row_mask:0xf bank_mask:0xf bound_ctrl:1
	v_fmac_f32_dpp v224, v122, v178 row_shl:14 row_mask:0xf bank_mask:0xf bound_ctrl:1
	v_fmac_f32_dpp v225, v123, v179 row_shl:14 row_mask:0xf bank_mask:0xf bound_ctrl:1
	v_fmac_f32_dpp v226, v124, v180 row_shl:14 row_mask:0xf bank_mask:0xf bound_ctrl:1
	v_fmac_f32_dpp v227, v125, v181 row_shl:14 row_mask:0xf bank_mask:0xf bound_ctrl:1
	v_fmac_f32_dpp v228, v102, v194 row_shl:14 row_mask:0xf bank_mask:0xf bound_ctrl:1
	v_fmac_f32_dpp v229, v103, v195 row_shl:14 row_mask:0xf bank_mask:0xf bound_ctrl:1
	v_fmac_f32_dpp v230, v104, v196 row_shl:14 row_mask:0xf bank_mask:0xf bound_ctrl:1
	v_fmac_f32_dpp v231, v105, v197 row_shl:14 row_mask:0xf bank_mask:0xf bound_ctrl:1
	v_pk_mul_f32 v[232:233], v[224:225], s[48:49] op_sel_hi:[1,0]
	v_pk_mul_f32 v[234:235], v[226:227], s[48:49] op_sel_hi:[1,0]
	v_exp_f32_e32 v232, v232
	v_exp_f32_e32 v233, v233
	v_exp_f32_e32 v234, v234
	v_exp_f32_e32 v235, v235
	v_pk_add_f32 v[232:233], v[232:233], 1.0 op_sel_hi:[1,0]
	v_pk_add_f32 v[234:235], v[234:235], 1.0 op_sel_hi:[1,0]
	v_rcp_f32_e32 v232, v232
	v_rcp_f32_e32 v233, v233
	v_rcp_f32_e32 v234, v234
	v_rcp_f32_e32 v235, v235
	v_lshl_add_u64 v[220:221], v[220:221], 0, s[96:97]
	v_pk_mul_f32 v[224:225], v[224:225], v[232:233]
	v_pk_mul_f32 v[226:227], v[226:227], v[234:235]
	v_pk_mul_f32 v[224:225], v[224:225], v[228:229]
	v_pk_mul_f32 v[226:227], v[226:227], v[230:231]
	v_cvt_pk_bf16_f32 v168, v224, v225
	v_cvt_pk_bf16_f32 v169, v226, v227
	global_store_dwordx2 v[220:221], v[168:169], off offset:32
	v_pk_fma_f32 v[224:225], v[98:99], v[186:187], v[190:191]
	v_pk_fma_f32 v[226:227], v[100:101], v[188:189], v[192:193]
	v_pk_fma_f32 v[228:229], v[74:75], v[202:203], v[206:207]
	v_pk_fma_f32 v[230:231], v[76:77], v[204:205], v[208:209]
	v_fmac_f32_dpp v224, v98, v182 row_shr:1 row_mask:0xf bank_mask:0xf bound_ctrl:1
	v_fmac_f32_dpp v225, v99, v183 row_shr:1 row_mask:0xf bank_mask:0xf bound_ctrl:1
	v_fmac_f32_dpp v226, v100, v184 row_shr:1 row_mask:0xf bank_mask:0xf bound_ctrl:1
	v_fmac_f32_dpp v227, v101, v185 row_shr:1 row_mask:0xf bank_mask:0xf bound_ctrl:1
	v_fmac_f32_dpp v228, v74, v198 row_shr:1 row_mask:0xf bank_mask:0xf bound_ctrl:1
	v_fmac_f32_dpp v229, v75, v199 row_shr:1 row_mask:0xf bank_mask:0xf bound_ctrl:1
	v_fmac_f32_dpp v230, v76, v200 row_shr:1 row_mask:0xf bank_mask:0xf bound_ctrl:1
	v_fmac_f32_dpp v231, v77, v201 row_shr:1 row_mask:0xf bank_mask:0xf bound_ctrl:1
	v_fmac_f32_dpp v224, v98, v178 row_shr:2 row_mask:0xf bank_mask:0xf bound_ctrl:1
	v_fmac_f32_dpp v225, v99, v179 row_shr:2 row_mask:0xf bank_mask:0xf bound_ctrl:1
	v_fmac_f32_dpp v226, v100, v180 row_shr:2 row_mask:0xf bank_mask:0xf bound_ctrl:1
	v_fmac_f32_dpp v227, v101, v181 row_shr:2 row_mask:0xf bank_mask:0xf bound_ctrl:1
	v_fmac_f32_dpp v228, v74, v194 row_shr:2 row_mask:0xf bank_mask:0xf bound_ctrl:1
	v_fmac_f32_dpp v229, v75, v195 row_shr:2 row_mask:0xf bank_mask:0xf bound_ctrl:1
	v_fmac_f32_dpp v230, v76, v196 row_shr:2 row_mask:0xf bank_mask:0xf bound_ctrl:1
	v_fmac_f32_dpp v231, v77, v197 row_shr:2 row_mask:0xf bank_mask:0xf bound_ctrl:1
	v_fmac_f32_dpp v224, v114, v182 row_shl:15 row_mask:0xf bank_mask:0xf bound_ctrl:1
	v_fmac_f32_dpp v225, v115, v183 row_shl:15 row_mask:0xf bank_mask:0xf bound_ctrl:1
	v_fmac_f32_dpp v226, v116, v184 row_shl:15 row_mask:0xf bank_mask:0xf bound_ctrl:1
	v_fmac_f32_dpp v227, v117, v185 row_shl:15 row_mask:0xf bank_mask:0xf bound_ctrl:1
	v_fmac_f32_dpp v228, v86, v198 row_shl:15 row_mask:0xf bank_mask:0xf bound_ctrl:1
	v_fmac_f32_dpp v229, v87, v199 row_shl:15 row_mask:0xf bank_mask:0xf bound_ctrl:1
	v_fmac_f32_dpp v230, v88, v200 row_shl:15 row_mask:0xf bank_mask:0xf bound_ctrl:1
	v_fmac_f32_dpp v231, v89, v201 row_shl:15 row_mask:0xf bank_mask:0xf bound_ctrl:1
	v_fmac_f32_dpp v224, v114, v178 row_shl:14 row_mask:0xf bank_mask:0xf bound_ctrl:1
	v_fmac_f32_dpp v225, v115, v179 row_shl:14 row_mask:0xf bank_mask:0xf bound_ctrl:1
	v_fmac_f32_dpp v226, v116, v180 row_shl:14 row_mask:0xf bank_mask:0xf bound_ctrl:1
	v_fmac_f32_dpp v227, v117, v181 row_shl:14 row_mask:0xf bank_mask:0xf bound_ctrl:1
	v_fmac_f32_dpp v228, v86, v194 row_shl:14 row_mask:0xf bank_mask:0xf bound_ctrl:1
	v_fmac_f32_dpp v229, v87, v195 row_shl:14 row_mask:0xf bank_mask:0xf bound_ctrl:1
	v_fmac_f32_dpp v230, v88, v196 row_shl:14 row_mask:0xf bank_mask:0xf bound_ctrl:1
	v_fmac_f32_dpp v231, v89, v197 row_shl:14 row_mask:0xf bank_mask:0xf bound_ctrl:1
	v_pk_mul_f32 v[232:233], v[224:225], s[48:49] op_sel_hi:[1,0]
	v_pk_mul_f32 v[234:235], v[226:227], s[48:49] op_sel_hi:[1,0]
	v_exp_f32_e32 v232, v232
	v_exp_f32_e32 v233, v233
	v_exp_f32_e32 v234, v234
	v_exp_f32_e32 v235, v235
	v_pk_add_f32 v[232:233], v[232:233], 1.0 op_sel_hi:[1,0]
	v_pk_add_f32 v[234:235], v[234:235], 1.0 op_sel_hi:[1,0]
	v_rcp_f32_e32 v232, v232
	v_rcp_f32_e32 v233, v233
	v_rcp_f32_e32 v234, v234
	v_rcp_f32_e32 v235, v235
	v_lshl_add_u64 v[220:221], v[220:221], 0, s[96:97]
	v_pk_mul_f32 v[224:225], v[224:225], v[232:233]
	v_pk_mul_f32 v[226:227], v[226:227], v[234:235]
	v_pk_mul_f32 v[224:225], v[224:225], v[228:229]
	v_pk_mul_f32 v[226:227], v[226:227], v[230:231]
	v_cvt_pk_bf16_f32 v168, v224, v225
	v_cvt_pk_bf16_f32 v169, v226, v227
	global_store_dwordx2 v[220:221], v[168:169], off offset:32
	s_add_u32 s94, s26, s85
	s_addc_u32 s95, s27, 0
	v_lshl_add_u64 v[222:223], s[94:95], 0, v[216:217]
	v_lshl_add_u64 v[246:247], s[94:95], 0, v[218:219]
	s_and_saveexec_b64 s[46:47], s[6:7]
	global_store_dwordx4 v[222:223], v[82:85], off offset:64
	global_store_dwordx4 v[246:247], v[66:69], off offset:64
	s_or_b64 exec, exec, s[46:47]
	v_pk_fma_f32 v[224:225], v[82:83], v[186:187], v[190:191]
	v_pk_fma_f32 v[226:227], v[84:85], v[188:189], v[192:193]
	v_pk_fma_f32 v[228:229], v[66:67], v[202:203], v[206:207]
	v_pk_fma_f32 v[230:231], v[68:69], v[204:205], v[208:209]
	v_fmac_f32_dpp v224, v82, v182 row_shr:1 row_mask:0xf bank_mask:0xf bound_ctrl:1
	v_fmac_f32_dpp v225, v83, v183 row_shr:1 row_mask:0xf bank_mask:0xf bound_ctrl:1
	v_fmac_f32_dpp v226, v84, v184 row_shr:1 row_mask:0xf bank_mask:0xf bound_ctrl:1
	v_fmac_f32_dpp v227, v85, v185 row_shr:1 row_mask:0xf bank_mask:0xf bound_ctrl:1
	v_fmac_f32_dpp v228, v66, v198 row_shr:1 row_mask:0xf bank_mask:0xf bound_ctrl:1
	v_fmac_f32_dpp v229, v67, v199 row_shr:1 row_mask:0xf bank_mask:0xf bound_ctrl:1
	v_fmac_f32_dpp v230, v68, v200 row_shr:1 row_mask:0xf bank_mask:0xf bound_ctrl:1
	v_fmac_f32_dpp v231, v69, v201 row_shr:1 row_mask:0xf bank_mask:0xf bound_ctrl:1
	v_fmac_f32_dpp v224, v82, v178 row_shr:2 row_mask:0xf bank_mask:0xf bound_ctrl:1
	v_fmac_f32_dpp v225, v83, v179 row_shr:2 row_mask:0xf bank_mask:0xf bound_ctrl:1
	v_fmac_f32_dpp v226, v84, v180 row_shr:2 row_mask:0xf bank_mask:0xf bound_ctrl:1
	v_fmac_f32_dpp v227, v85, v181 row_shr:2 row_mask:0xf bank_mask:0xf bound_ctrl:1
	v_fmac_f32_dpp v228, v66, v194 row_shr:2 row_mask:0xf bank_mask:0xf bound_ctrl:1
	v_fmac_f32_dpp v229, v67, v195 row_shr:2 row_mask:0xf bank_mask:0xf bound_ctrl:1
	v_fmac_f32_dpp v230, v68, v196 row_shr:2 row_mask:0xf bank_mask:0xf bound_ctrl:1
	v_fmac_f32_dpp v231, v69, v197 row_shr:2 row_mask:0xf bank_mask:0xf bound_ctrl:1
	v_fmac_f32_dpp v224, v98, v182 row_shl:15 row_mask:0xf bank_mask:0xf bound_ctrl:1
	v_fmac_f32_dpp v225, v99, v183 row_shl:15 row_mask:0xf bank_mask:0xf bound_ctrl:1
	v_fmac_f32_dpp v226, v100, v184 row_shl:15 row_mask:0xf bank_mask:0xf bound_ctrl:1
	v_fmac_f32_dpp v227, v101, v185 row_shl:15 row_mask:0xf bank_mask:0xf bound_ctrl:1
	v_fmac_f32_dpp v228, v74, v198 row_shl:15 row_mask:0xf bank_mask:0xf bound_ctrl:1
	v_fmac_f32_dpp v229, v75, v199 row_shl:15 row_mask:0xf bank_mask:0xf bound_ctrl:1
	v_fmac_f32_dpp v230, v76, v200 row_shl:15 row_mask:0xf bank_mask:0xf bound_ctrl:1
	v_fmac_f32_dpp v231, v77, v201 row_shl:15 row_mask:0xf bank_mask:0xf bound_ctrl:1
	v_fmac_f32_dpp v224, v98, v178 row_shl:14 row_mask:0xf bank_mask:0xf bound_ctrl:1
	v_fmac_f32_dpp v225, v99, v179 row_shl:14 row_mask:0xf bank_mask:0xf bound_ctrl:1
	v_fmac_f32_dpp v226, v100, v180 row_shl:14 row_mask:0xf bank_mask:0xf bound_ctrl:1
	v_fmac_f32_dpp v227, v101, v181 row_shl:14 row_mask:0xf bank_mask:0xf bound_ctrl:1
	v_fmac_f32_dpp v228, v74, v194 row_shl:14 row_mask:0xf bank_mask:0xf bound_ctrl:1
	v_fmac_f32_dpp v229, v75, v195 row_shl:14 row_mask:0xf bank_mask:0xf bound_ctrl:1
	v_fmac_f32_dpp v230, v76, v196 row_shl:14 row_mask:0xf bank_mask:0xf bound_ctrl:1
	v_fmac_f32_dpp v231, v77, v197 row_shl:14 row_mask:0xf bank_mask:0xf bound_ctrl:1
	v_pk_mul_f32 v[232:233], v[224:225], s[48:49] op_sel_hi:[1,0]
	v_pk_mul_f32 v[234:235], v[226:227], s[48:49] op_sel_hi:[1,0]
	v_exp_f32_e32 v232, v232
	v_exp_f32_e32 v233, v233
	v_exp_f32_e32 v234, v234
	v_exp_f32_e32 v235, v235
	v_pk_add_f32 v[232:233], v[232:233], 1.0 op_sel_hi:[1,0]
	v_pk_add_f32 v[234:235], v[234:235], 1.0 op_sel_hi:[1,0]
	v_rcp_f32_e32 v232, v232
	v_rcp_f32_e32 v233, v233
	v_rcp_f32_e32 v234, v234
	v_rcp_f32_e32 v235, v235
	v_lshl_add_u64 v[220:221], v[220:221], 0, s[96:97]
	v_pk_mul_f32 v[224:225], v[224:225], v[232:233]
	v_pk_mul_f32 v[226:227], v[226:227], v[234:235]
	v_pk_mul_f32 v[224:225], v[224:225], v[228:229]
	v_pk_mul_f32 v[226:227], v[226:227], v[230:231]
	v_cvt_pk_bf16_f32 v168, v224, v225
	v_cvt_pk_bf16_f32 v169, v226, v227
	global_store_dwordx2 v[220:221], v[168:169], off offset:32
	s_add_i32 s84, s39, 2
	s_mul_i32 s85, s84, 0xb0000
	s_add_u32 s94, s22, s85
	s_addc_u32 s95, s23, 0
	v_lshl_add_u64 v[220:221], s[94:95], 0, v[210:211]
	s_mul_i32 s85, s84, 0x16000
	s_add_u32 s94, s24, s85
	s_addc_u32 s95, s25, 0
	v_lshl_add_u64 v[222:223], s[94:95], 0, v[212:213]
	v_lshl_add_u64 v[246:247], s[94:95], 0, v[214:215]
	s_and_saveexec_b64 s[46:47], s[4:5]
	global_store_dwordx4 v[222:223], v[58:61], off offset:64
	global_store_dwordx4 v[246:247], v[38:41], off offset:64
	s_or_b64 exec, exec, s[46:47]
	v_pk_fma_f32 v[224:225], v[58:59], v[186:187], v[190:191]
	v_pk_fma_f32 v[226:227], v[60:61], v[188:189], v[192:193]
	v_pk_fma_f32 v[228:229], v[38:39], v[202:203], v[206:207]
	v_pk_fma_f32 v[230:231], v[40:41], v[204:205], v[208:209]
	v_fmac_f32_dpp v224, v58, v182 row_shr:1 row_mask:0xf bank_mask:0xf bound_ctrl:1
	v_fmac_f32_dpp v225, v59, v183 row_shr:1 row_mask:0xf bank_mask:0xf bound_ctrl:1
	v_fmac_f32_dpp v226, v60, v184 row_shr:1 row_mask:0xf bank_mask:0xf bound_ctrl:1
	v_fmac_f32_dpp v227, v61, v185 row_shr:1 row_mask:0xf bank_mask:0xf bound_ctrl:1
	v_fmac_f32_dpp v228, v38, v198 row_shr:1 row_mask:0xf bank_mask:0xf bound_ctrl:1
	v_fmac_f32_dpp v229, v39, v199 row_shr:1 row_mask:0xf bank_mask:0xf bound_ctrl:1
	v_fmac_f32_dpp v230, v40, v200 row_shr:1 row_mask:0xf bank_mask:0xf bound_ctrl:1
	v_fmac_f32_dpp v231, v41, v201 row_shr:1 row_mask:0xf bank_mask:0xf bound_ctrl:1
	v_fmac_f32_dpp v224, v58, v178 row_shr:2 row_mask:0xf bank_mask:0xf bound_ctrl:1
	v_fmac_f32_dpp v225, v59, v179 row_shr:2 row_mask:0xf bank_mask:0xf bound_ctrl:1
	v_fmac_f32_dpp v226, v60, v180 row_shr:2 row_mask:0xf bank_mask:0xf bound_ctrl:1
	v_fmac_f32_dpp v227, v61, v181 row_shr:2 row_mask:0xf bank_mask:0xf bound_ctrl:1
	v_fmac_f32_dpp v228, v38, v194 row_shr:2 row_mask:0xf bank_mask:0xf bound_ctrl:1
	v_fmac_f32_dpp v229, v39, v195 row_shr:2 row_mask:0xf bank_mask:0xf bound_ctrl:1
	v_fmac_f32_dpp v230, v40, v196 row_shr:2 row_mask:0xf bank_mask:0xf bound_ctrl:1
	v_fmac_f32_dpp v231, v41, v197 row_shr:2 row_mask:0xf bank_mask:0xf bound_ctrl:1
	v_pk_mul_f32 v[232:233], v[224:225], s[48:49] op_sel_hi:[1,0]
	v_pk_mul_f32 v[234:235], v[226:227], s[48:49] op_sel_hi:[1,0]
	v_exp_f32_e32 v232, v232
	v_exp_f32_e32 v233, v233
	v_exp_f32_e32 v234, v234
	v_exp_f32_e32 v235, v235
	v_pk_add_f32 v[232:233], v[232:233], 1.0 op_sel_hi:[1,0]
	v_pk_add_f32 v[234:235], v[234:235], 1.0 op_sel_hi:[1,0]
	v_rcp_f32_e32 v232, v232
	v_rcp_f32_e32 v233, v233
	v_rcp_f32_e32 v234, v234
	v_rcp_f32_e32 v235, v235
	v_pk_mul_f32 v[224:225], v[224:225], v[232:233]
	v_pk_mul_f32 v[226:227], v[226:227], v[234:235]
	v_pk_mul_f32 v[224:225], v[224:225], v[228:229]
	v_pk_mul_f32 v[226:227], v[226:227], v[230:231]
	v_cvt_pk_bf16_f32 v168, v224, v225
	v_cvt_pk_bf16_f32 v169, v226, v227
	s_and_saveexec_b64 s[46:47], s[8:9]
	global_store_dwordx2 v[220:221], v[168:169], off offset:32
	s_or_b64 exec, exec, s[46:47]
	v_pk_fma_f32 v[224:225], v[50:51], v[186:187], v[190:191]
	v_pk_fma_f32 v[226:227], v[52:53], v[188:189], v[192:193]
	v_pk_fma_f32 v[228:229], v[22:23], v[202:203], v[206:207]
	v_pk_fma_f32 v[230:231], v[24:25], v[204:205], v[208:209]
	v_fmac_f32_dpp v224, v50, v182 row_shr:1 row_mask:0xf bank_mask:0xf bound_ctrl:1
	v_fmac_f32_dpp v225, v51, v183 row_shr:1 row_mask:0xf bank_mask:0xf bound_ctrl:1
	v_fmac_f32_dpp v226, v52, v184 row_shr:1 row_mask:0xf bank_mask:0xf bound_ctrl:1
	v_fmac_f32_dpp v227, v53, v185 row_shr:1 row_mask:0xf bank_mask:0xf bound_ctrl:1
	v_fmac_f32_dpp v228, v22, v198 row_shr:1 row_mask:0xf bank_mask:0xf bound_ctrl:1
	v_fmac_f32_dpp v229, v23, v199 row_shr:1 row_mask:0xf bank_mask:0xf bound_ctrl:1
	v_fmac_f32_dpp v230, v24, v200 row_shr:1 row_mask:0xf bank_mask:0xf bound_ctrl:1
	v_fmac_f32_dpp v231, v25, v201 row_shr:1 row_mask:0xf bank_mask:0xf bound_ctrl:1
	v_fmac_f32_dpp v224, v50, v178 row_shr:2 row_mask:0xf bank_mask:0xf bound_ctrl:1
	v_fmac_f32_dpp v225, v51, v179 row_shr:2 row_mask:0xf bank_mask:0xf bound_ctrl:1
	v_fmac_f32_dpp v226, v52, v180 row_shr:2 row_mask:0xf bank_mask:0xf bound_ctrl:1
	v_fmac_f32_dpp v227, v53, v181 row_shr:2 row_mask:0xf bank_mask:0xf bound_ctrl:1
	v_fmac_f32_dpp v228, v22, v194 row_shr:2 row_mask:0xf bank_mask:0xf bound_ctrl:1
	v_fmac_f32_dpp v229, v23, v195 row_shr:2 row_mask:0xf bank_mask:0xf bound_ctrl:1
	v_fmac_f32_dpp v230, v24, v196 row_shr:2 row_mask:0xf bank_mask:0xf bound_ctrl:1
	v_fmac_f32_dpp v231, v25, v197 row_shr:2 row_mask:0xf bank_mask:0xf bound_ctrl:1
	v_fmac_f32_dpp v224, v58, v182 row_shl:15 row_mask:0xf bank_mask:0xf bound_ctrl:1
	v_fmac_f32_dpp v225, v59, v183 row_shl:15 row_mask:0xf bank_mask:0xf bound_ctrl:1
	v_fmac_f32_dpp v226, v60, v184 row_shl:15 row_mask:0xf bank_mask:0xf bound_ctrl:1
	v_fmac_f32_dpp v227, v61, v185 row_shl:15 row_mask:0xf bank_mask:0xf bound_ctrl:1
	v_fmac_f32_dpp v228, v38, v198 row_shl:15 row_mask:0xf bank_mask:0xf bound_ctrl:1
	v_fmac_f32_dpp v229, v39, v199 row_shl:15 row_mask:0xf bank_mask:0xf bound_ctrl:1
	v_fmac_f32_dpp v230, v40, v200 row_shl:15 row_mask:0xf bank_mask:0xf bound_ctrl:1
	v_fmac_f32_dpp v231, v41, v201 row_shl:15 row_mask:0xf bank_mask:0xf bound_ctrl:1
	v_fmac_f32_dpp v224, v58, v178 row_shl:14 row_mask:0xf bank_mask:0xf bound_ctrl:1
	v_fmac_f32_dpp v225, v59, v179 row_shl:14 row_mask:0xf bank_mask:0xf bound_ctrl:1
	v_fmac_f32_dpp v226, v60, v180 row_shl:14 row_mask:0xf bank_mask:0xf bound_ctrl:1
	v_fmac_f32_dpp v227, v61, v181 row_shl:14 row_mask:0xf bank_mask:0xf bound_ctrl:1
	v_fmac_f32_dpp v228, v38, v194 row_shl:14 row_mask:0xf bank_mask:0xf bound_ctrl:1
	v_fmac_f32_dpp v229, v39, v195 row_shl:14 row_mask:0xf bank_mask:0xf bound_ctrl:1
	v_fmac_f32_dpp v230, v40, v196 row_shl:14 row_mask:0xf bank_mask:0xf bound_ctrl:1
	v_fmac_f32_dpp v231, v41, v197 row_shl:14 row_mask:0xf bank_mask:0xf bound_ctrl:1
	v_pk_mul_f32 v[232:233], v[224:225], s[48:49] op_sel_hi:[1,0]
	v_pk_mul_f32 v[234:235], v[226:227], s[48:49] op_sel_hi:[1,0]
	v_exp_f32_e32 v232, v232
	v_exp_f32_e32 v233, v233
	v_exp_f32_e32 v234, v234
	v_exp_f32_e32 v235, v235
	v_pk_add_f32 v[232:233], v[232:233], 1.0 op_sel_hi:[1,0]
	v_pk_add_f32 v[234:235], v[234:235], 1.0 op_sel_hi:[1,0]
	v_rcp_f32_e32 v232, v232
	v_rcp_f32_e32 v233, v233
	v_rcp_f32_e32 v234, v234
	v_rcp_f32_e32 v235, v235
	v_lshl_add_u64 v[220:221], v[220:221], 0, s[96:97]
	v_pk_mul_f32 v[224:225], v[224:225], v[232:233]
	v_pk_mul_f32 v[226:227], v[226:227], v[234:235]
	v_pk_mul_f32 v[224:225], v[224:225], v[228:229]
	v_pk_mul_f32 v[226:227], v[226:227], v[230:231]
	v_cvt_pk_bf16_f32 v168, v224, v225
	v_cvt_pk_bf16_f32 v169, v226, v227
	global_store_dwordx2 v[220:221], v[168:169], off offset:32
	v_pk_fma_f32 v[224:225], v[34:35], v[186:187], v[190:191]
	v_pk_fma_f32 v[226:227], v[36:37], v[188:189], v[192:193]
	v_pk_fma_f32 v[228:229], v[10:11], v[202:203], v[206:207]
	v_pk_fma_f32 v[230:231], v[12:13], v[204:205], v[208:209]
	v_fmac_f32_dpp v224, v34, v182 row_shr:1 row_mask:0xf bank_mask:0xf bound_ctrl:1
	v_fmac_f32_dpp v225, v35, v183 row_shr:1 row_mask:0xf bank_mask:0xf bound_ctrl:1
	v_fmac_f32_dpp v226, v36, v184 row_shr:1 row_mask:0xf bank_mask:0xf bound_ctrl:1
	v_fmac_f32_dpp v227, v37, v185 row_shr:1 row_mask:0xf bank_mask:0xf bound_ctrl:1
	v_fmac_f32_dpp v228, v10, v198 row_shr:1 row_mask:0xf bank_mask:0xf bound_ctrl:1
	v_fmac_f32_dpp v229, v11, v199 row_shr:1 row_mask:0xf bank_mask:0xf bound_ctrl:1
	v_fmac_f32_dpp v230, v12, v200 row_shr:1 row_mask:0xf bank_mask:0xf bound_ctrl:1
	v_fmac_f32_dpp v231, v13, v201 row_shr:1 row_mask:0xf bank_mask:0xf bound_ctrl:1
	v_fmac_f32_dpp v224, v34, v178 row_shr:2 row_mask:0xf bank_mask:0xf bound_ctrl:1
	v_fmac_f32_dpp v225, v35, v179 row_shr:2 row_mask:0xf bank_mask:0xf bound_ctrl:1
	v_fmac_f32_dpp v226, v36, v180 row_shr:2 row_mask:0xf bank_mask:0xf bound_ctrl:1
	v_fmac_f32_dpp v227, v37, v181 row_shr:2 row_mask:0xf bank_mask:0xf bound_ctrl:1
	v_fmac_f32_dpp v228, v10, v194 row_shr:2 row_mask:0xf bank_mask:0xf bound_ctrl:1
	v_fmac_f32_dpp v229, v11, v195 row_shr:2 row_mask:0xf bank_mask:0xf bound_ctrl:1
	v_fmac_f32_dpp v230, v12, v196 row_shr:2 row_mask:0xf bank_mask:0xf bound_ctrl:1
	v_fmac_f32_dpp v231, v13, v197 row_shr:2 row_mask:0xf bank_mask:0xf bound_ctrl:1
	v_fmac_f32_dpp v224, v50, v182 row_shl:15 row_mask:0xf bank_mask:0xf bound_ctrl:1
	v_fmac_f32_dpp v225, v51, v183 row_shl:15 row_mask:0xf bank_mask:0xf bound_ctrl:1
	v_fmac_f32_dpp v226, v52, v184 row_shl:15 row_mask:0xf bank_mask:0xf bound_ctrl:1
	v_fmac_f32_dpp v227, v53, v185 row_shl:15 row_mask:0xf bank_mask:0xf bound_ctrl:1
	v_fmac_f32_dpp v228, v22, v198 row_shl:15 row_mask:0xf bank_mask:0xf bound_ctrl:1
	v_fmac_f32_dpp v229, v23, v199 row_shl:15 row_mask:0xf bank_mask:0xf bound_ctrl:1
	v_fmac_f32_dpp v230, v24, v200 row_shl:15 row_mask:0xf bank_mask:0xf bound_ctrl:1
	v_fmac_f32_dpp v231, v25, v201 row_shl:15 row_mask:0xf bank_mask:0xf bound_ctrl:1
	v_fmac_f32_dpp v224, v50, v178 row_shl:14 row_mask:0xf bank_mask:0xf bound_ctrl:1
	v_fmac_f32_dpp v225, v51, v179 row_shl:14 row_mask:0xf bank_mask:0xf bound_ctrl:1
	v_fmac_f32_dpp v226, v52, v180 row_shl:14 row_mask:0xf bank_mask:0xf bound_ctrl:1
	v_fmac_f32_dpp v227, v53, v181 row_shl:14 row_mask:0xf bank_mask:0xf bound_ctrl:1
	v_fmac_f32_dpp v228, v22, v194 row_shl:14 row_mask:0xf bank_mask:0xf bound_ctrl:1
	v_fmac_f32_dpp v229, v23, v195 row_shl:14 row_mask:0xf bank_mask:0xf bound_ctrl:1
	v_fmac_f32_dpp v230, v24, v196 row_shl:14 row_mask:0xf bank_mask:0xf bound_ctrl:1
	v_fmac_f32_dpp v231, v25, v197 row_shl:14 row_mask:0xf bank_mask:0xf bound_ctrl:1
	v_pk_mul_f32 v[232:233], v[224:225], s[48:49] op_sel_hi:[1,0]
	v_pk_mul_f32 v[234:235], v[226:227], s[48:49] op_sel_hi:[1,0]
	v_exp_f32_e32 v232, v232
	v_exp_f32_e32 v233, v233
	v_exp_f32_e32 v234, v234
	v_exp_f32_e32 v235, v235
	v_pk_add_f32 v[232:233], v[232:233], 1.0 op_sel_hi:[1,0]
	v_pk_add_f32 v[234:235], v[234:235], 1.0 op_sel_hi:[1,0]
	v_rcp_f32_e32 v232, v232
	v_rcp_f32_e32 v233, v233
	v_rcp_f32_e32 v234, v234
	v_rcp_f32_e32 v235, v235
	v_lshl_add_u64 v[220:221], v[220:221], 0, s[96:97]
	v_pk_mul_f32 v[224:225], v[224:225], v[232:233]
	v_pk_mul_f32 v[226:227], v[226:227], v[234:235]
	v_pk_mul_f32 v[224:225], v[224:225], v[228:229]
	v_pk_mul_f32 v[226:227], v[226:227], v[230:231]
	v_cvt_pk_bf16_f32 v168, v224, v225
	v_cvt_pk_bf16_f32 v169, v226, v227
	global_store_dwordx2 v[220:221], v[168:169], off offset:32
	s_add_u32 s94, s26, s85
	s_addc_u32 s95, s27, 0
	v_lshl_add_u64 v[222:223], s[94:95], 0, v[216:217]
	v_lshl_add_u64 v[246:247], s[94:95], 0, v[218:219]
	s_and_saveexec_b64 s[46:47], s[6:7]
	global_store_dwordx4 v[222:223], v[18:21], off offset:64
	global_store_dwordx4 v[246:247], v[2:5], off offset:64
	s_or_b64 exec, exec, s[46:47]
	v_pk_fma_f32 v[224:225], v[18:19], v[186:187], v[190:191]
	v_pk_fma_f32 v[226:227], v[20:21], v[188:189], v[192:193]
	v_pk_fma_f32 v[228:229], v[2:3], v[202:203], v[206:207]
	v_pk_fma_f32 v[230:231], v[4:5], v[204:205], v[208:209]
	v_fmac_f32_dpp v224, v18, v182 row_shr:1 row_mask:0xf bank_mask:0xf bound_ctrl:1
	v_fmac_f32_dpp v225, v19, v183 row_shr:1 row_mask:0xf bank_mask:0xf bound_ctrl:1
	v_fmac_f32_dpp v226, v20, v184 row_shr:1 row_mask:0xf bank_mask:0xf bound_ctrl:1
	v_fmac_f32_dpp v227, v21, v185 row_shr:1 row_mask:0xf bank_mask:0xf bound_ctrl:1
	v_fmac_f32_dpp v228, v2, v198 row_shr:1 row_mask:0xf bank_mask:0xf bound_ctrl:1
	v_fmac_f32_dpp v229, v3, v199 row_shr:1 row_mask:0xf bank_mask:0xf bound_ctrl:1
	v_fmac_f32_dpp v230, v4, v200 row_shr:1 row_mask:0xf bank_mask:0xf bound_ctrl:1
	v_fmac_f32_dpp v231, v5, v201 row_shr:1 row_mask:0xf bank_mask:0xf bound_ctrl:1
	v_fmac_f32_dpp v224, v18, v178 row_shr:2 row_mask:0xf bank_mask:0xf bound_ctrl:1
	v_fmac_f32_dpp v225, v19, v179 row_shr:2 row_mask:0xf bank_mask:0xf bound_ctrl:1
	v_fmac_f32_dpp v226, v20, v180 row_shr:2 row_mask:0xf bank_mask:0xf bound_ctrl:1
	v_fmac_f32_dpp v227, v21, v181 row_shr:2 row_mask:0xf bank_mask:0xf bound_ctrl:1
	v_fmac_f32_dpp v228, v2, v194 row_shr:2 row_mask:0xf bank_mask:0xf bound_ctrl:1
	v_fmac_f32_dpp v229, v3, v195 row_shr:2 row_mask:0xf bank_mask:0xf bound_ctrl:1
	v_fmac_f32_dpp v230, v4, v196 row_shr:2 row_mask:0xf bank_mask:0xf bound_ctrl:1
	v_fmac_f32_dpp v231, v5, v197 row_shr:2 row_mask:0xf bank_mask:0xf bound_ctrl:1
	v_fmac_f32_dpp v224, v34, v182 row_shl:15 row_mask:0xf bank_mask:0xf bound_ctrl:1
	v_fmac_f32_dpp v225, v35, v183 row_shl:15 row_mask:0xf bank_mask:0xf bound_ctrl:1
	v_fmac_f32_dpp v226, v36, v184 row_shl:15 row_mask:0xf bank_mask:0xf bound_ctrl:1
	v_fmac_f32_dpp v227, v37, v185 row_shl:15 row_mask:0xf bank_mask:0xf bound_ctrl:1
	v_fmac_f32_dpp v228, v10, v198 row_shl:15 row_mask:0xf bank_mask:0xf bound_ctrl:1
	v_fmac_f32_dpp v229, v11, v199 row_shl:15 row_mask:0xf bank_mask:0xf bound_ctrl:1
	v_fmac_f32_dpp v230, v12, v200 row_shl:15 row_mask:0xf bank_mask:0xf bound_ctrl:1
	v_fmac_f32_dpp v231, v13, v201 row_shl:15 row_mask:0xf bank_mask:0xf bound_ctrl:1
	v_fmac_f32_dpp v224, v34, v178 row_shl:14 row_mask:0xf bank_mask:0xf bound_ctrl:1
	v_fmac_f32_dpp v225, v35, v179 row_shl:14 row_mask:0xf bank_mask:0xf bound_ctrl:1
	v_fmac_f32_dpp v226, v36, v180 row_shl:14 row_mask:0xf bank_mask:0xf bound_ctrl:1
	v_fmac_f32_dpp v227, v37, v181 row_shl:14 row_mask:0xf bank_mask:0xf bound_ctrl:1
	v_fmac_f32_dpp v228, v10, v194 row_shl:14 row_mask:0xf bank_mask:0xf bound_ctrl:1
	v_fmac_f32_dpp v229, v11, v195 row_shl:14 row_mask:0xf bank_mask:0xf bound_ctrl:1
	v_fmac_f32_dpp v230, v12, v196 row_shl:14 row_mask:0xf bank_mask:0xf bound_ctrl:1
	v_fmac_f32_dpp v231, v13, v197 row_shl:14 row_mask:0xf bank_mask:0xf bound_ctrl:1
	v_pk_mul_f32 v[232:233], v[224:225], s[48:49] op_sel_hi:[1,0]
	v_pk_mul_f32 v[234:235], v[226:227], s[48:49] op_sel_hi:[1,0]
	v_exp_f32_e32 v232, v232
	v_exp_f32_e32 v233, v233
	v_exp_f32_e32 v234, v234
	v_exp_f32_e32 v235, v235
	v_pk_add_f32 v[232:233], v[232:233], 1.0 op_sel_hi:[1,0]
	v_pk_add_f32 v[234:235], v[234:235], 1.0 op_sel_hi:[1,0]
	v_rcp_f32_e32 v232, v232
	v_rcp_f32_e32 v233, v233
	v_rcp_f32_e32 v234, v234
	v_rcp_f32_e32 v235, v235
	v_lshl_add_u64 v[220:221], v[220:221], 0, s[96:97]
	v_pk_mul_f32 v[224:225], v[224:225], v[232:233]
	v_pk_mul_f32 v[226:227], v[226:227], v[234:235]
	v_pk_mul_f32 v[224:225], v[224:225], v[228:229]
	v_pk_mul_f32 v[226:227], v[226:227], v[230:231]
	v_cvt_pk_bf16_f32 v168, v224, v225
	v_cvt_pk_bf16_f32 v169, v226, v227
	global_store_dwordx2 v[220:221], v[168:169], off offset:32
	s_mov_b32 s32, 1
	s_branch .LBB0_1094
